# nt hint also on the P0 f32 weight-copy loads (w_in, w_mem_kv, w_out tiles)
# baseline (speedup 1.0000x reference)
; #define GAS __attribute__((address_space(1)))
; #define LAS __attribute__((address_space(3)))
; #define LDS_WAIT() asm volatile("s_waitcnt lgkmcnt(0)" ::: "memory")
; __device__ __forceinline__ unsigned pk2(float lo, float hi) { const pkf2_t v = {lo, hi}; const pkb2_t b = __builtin_convertvector(v, pkb2_t); return __builtin_bit_cast(unsigned, b); }
; __device__ __forceinline__ void p0_transpose_item2(const float* W, int K, int N, bf16* WT, int dst_row0, const float* gain, LAS float* scr, int kb, int nb, int lane) {
;     const int k0 = 64 * kb, n0 = 32 * nb;
;     const int c = lane & 7; float gg[8];
;     { const int kk = lane >> 3, n4 = (lane & 7) * 4; f32x4 v[8];
; #pragma unroll
;       for (int i = 0; i < 8; ++i) v[i] = *(const GAS f32x4*)(W + (size_t)(k0 + kk + 8 * i) * N + n0 + n4);
; #pragma unroll
;       for (int e = 0; e < 8; ++e) gg[e] = gain[k0 + 8 * c + e];
; #pragma unroll
;       for (int i = 0; i < 8; ++i) { LAS float* d = scr + (kk + 8 * i) * 33 + n4; d[0] = v[i][0]; d[1] = v[i][1]; d[2] = v[i][2]; d[3] = v[i][3]; } }
;     LDS_WAIT(); asm volatile("" ::: "memory");
; #pragma unroll
;     for (int j = 0; j < 4; ++j) { const int n = (lane >> 3) + 8 * j; const LAS float* s = scr + (8 * c) * 33 + n;
;         v4u o; o.x = pk2(s[0 * 33] * gg[0], s[1 * 33] * gg[1]); o.y = pk2(s[2 * 33] * gg[2], s[3 * 33] * gg[3]); o.z = pk2(s[4 * 33] * gg[4], s[5 * 33] * gg[5]); o.w = pk2(s[6 * 33] * gg[6], s[7 * 33] * gg[7]);
;         *(GAS v4u*)(WT + (size_t)(dst_row0 + n) * K + k0 + 8 * c) = o; }
;     LDS_WAIT(); asm volatile("" ::: "memory");
; }
; __device__ __forceinline__ void p0_wup_item(Frame& F, LAS float* scr, int r) {
;     const int nblk = 2 * DFF / 32, kb = r / nblk, nb = r % nblk, n0 = 32 * nb, j = n0 < DFF ? n0 : n0 - DFF;
;     p0_transpose_item2(F.w_up, D, 2 * DFF, F.WUP, (j >> 7) * 256 + (j & 127) + (n0 < DFF ? 0 : 128), F.ln2_g, scr, kb, nb, F.lane);
.LBB0_51:
	s_cmpk_gt_i32 s18, 0x4ff
	s_mov_b64 s[2:3], -1
	s_cbranch_scc0 .LBB0_57
	s_cmpk_gt_u32 s18, 0x5ff
	s_cbranch_scc0 .LBB0_54
	s_add_i32 s2, s18, 0xfa00
	s_and_b32 s3, s2, 0xffff
	s_mul_i32 s3, s3, 0xba2f
	s_lshr_b32 s3, s3, 23
	s_mul_i32 s4, s3, 0xb0
	s_sub_i32 s2, s2, s4
	s_lshl_b32 s4, s2, 5
	s_and_b32 s4, s4, 0xffe0
	s_and_b32 s2, s2, 0xffff
	s_add_i32 s5, s4, 0xfffff500
	s_cmpk_lt_u32 s2, 0x58
	s_cselect_b32 s2, s4, s5
	s_cselect_b32 s5, 0, 0x80
	s_lshl_b32 s19, s3, 6
	v_or_b32_e32 v2, s19, v16
	s_lshl_b32 s6, s4, 2
	v_lshl_add_u64 v[38:39], v[4:5], 0, s[6:7]
	v_mul_u32_u24_e32 v2, 0x5800, v2
	v_lshl_add_u64 v[66:67], v[38:39], 0, v[2:3]
	s_mov_b32 s4, 0x2c000
	v_add_co_u32_e32 v42, vcc, s4, v66
	s_mov_b32 s4, 0x58000
	s_nop 0
	v_addc_co_u32_e32 v43, vcc, 0, v67, vcc
	v_add_co_u32_e32 v46, vcc, s4, v66
	s_mov_b32 s4, 0x84000
	s_nop 0
	v_addc_co_u32_e32 v47, vcc, 0, v67, vcc
	v_add_co_u32_e32 v50, vcc, s4, v66
	s_mov_b32 s4, 0xb0000
	s_nop 0
	v_addc_co_u32_e32 v51, vcc, 0, v67, vcc
	s_waitcnt lgkmcnt(0)
	v_add_co_u32_e32 v54, vcc, s4, v66
	s_mov_b32 s4, 0xdc000
	s_nop 0
	v_addc_co_u32_e32 v55, vcc, 0, v67, vcc
	v_add_co_u32_e32 v58, vcc, s4, v66
	global_load_dwordx4 v[38:41], v[66:67], off nt
	s_nop 0
	global_load_dwordx4 v[42:45], v[42:43], off nt
	v_addc_co_u32_e32 v59, vcc, 0, v67, vcc
	global_load_dwordx4 v[46:49], v[46:47], off nt
	s_nop 0
	global_load_dwordx4 v[50:53], v[50:51], off nt
	s_nop 0
	global_load_dwordx4 v[54:57], v[54:55], off nt
	s_nop 0
	global_load_dwordx4 v[58:61], v[58:59], off nt
	s_mov_b32 s4, 0x108000
	v_add_co_u32_e32 v62, vcc, s4, v66
	v_or_b32_e32 v2, s19, v17
	s_nop 0
	v_addc_co_u32_e32 v63, vcc, 0, v67, vcc
	v_add_co_u32_e32 v66, vcc, s16, v66
	v_lshlrev_b32_e32 v2, 2, v2
	s_nop 0
	v_addc_co_u32_e32 v67, vcc, 0, v67, vcc
	global_load_dwordx4 v[62:65], v[62:63], off nt
	s_lshl_b32 s4, s2, 1
	global_load_dwordx4 v[66:69], v[66:67], off nt
	s_nop 0
	global_load_dwordx4 v[70:73], v2, s[38:39] nt
	global_load_dwordx4 v[74:77], v2, s[38:39] offset:16 nt
	s_and_b32 s2, s2, 0x60
	s_lshl_b32 s6, s3, 7
	s_and_b32 s3, s4, 0xffffff00
	s_or_b32 s2, s2, s5
	s_or_b32 s2, s2, s3
	v_lshl_add_u64 v[78:79], v[6:7], 0, s[6:7]
	s_waitcnt vmcnt(9)
	ds_write2_b32 v22, v38, v39 offset1:1
	ds_write2_b32 v22, v40, v41 offset0:2 offset1:3
	s_waitcnt vmcnt(8)
	ds_write2_b32 v23, v42, v43 offset1:1
	ds_write2_b32 v24, v44, v45 offset1:1
	s_waitcnt vmcnt(7)
	ds_write2_b32 v25, v46, v47 offset1:1
	ds_write2_b32 v26, v48, v49 offset1:1
	s_waitcnt vmcnt(6)
	ds_write2_b32 v27, v50, v51 offset1:1
	ds_write2_b32 v28, v52, v53 offset1:1
	s_waitcnt vmcnt(5)
	ds_write2_b32 v29, v54, v55 offset1:1
	ds_write2_b32 v30, v56, v57 offset1:1
	s_waitcnt vmcnt(4)
	ds_write2_b32 v31, v58, v59 offset1:1
	ds_write2_b32 v32, v60, v61 offset1:1
	s_waitcnt vmcnt(3)
	ds_write2_b32 v33, v62, v63 offset1:1
	ds_write2_b32 v34, v64, v65 offset1:1
	s_waitcnt vmcnt(2)
	ds_write2_b32 v35, v66, v67 offset1:1
	ds_write2_b32 v36, v68, v69 offset1:1
	s_waitcnt lgkmcnt(0)
	ds_read2_b32 v[42:43], v21 offset0:33 offset1:41
	ds_read2_b32 v[44:45], v21 offset1:8
	ds_read2_b32 v[46:47], v21 offset0:66 offset1:74
	ds_read2_b32 v[48:49], v21 offset0:99 offset1:107
	ds_read2_b32 v[50:51], v21 offset0:132 offset1:140
	ds_read2_b32 v[52:53], v21 offset0:165 offset1:173
	ds_read2_b32 v[54:55], v21 offset0:198 offset1:206
	ds_read2_b32 v[56:57], v21 offset0:231 offset1:239
	s_waitcnt lgkmcnt(6)
	v_mov_b32_e32 v38, v44
	v_mov_b32_e32 v39, v42
	s_waitcnt lgkmcnt(5)
	v_mov_b32_e32 v40, v46
	s_waitcnt lgkmcnt(4)
	v_mov_b32_e32 v41, v48
	s_waitcnt lgkmcnt(3)
	v_mov_b32_e32 v58, v50
	s_waitcnt lgkmcnt(2)
	v_mov_b32_e32 v59, v52
	s_waitcnt lgkmcnt(1)
	v_mov_b32_e32 v60, v54
	s_waitcnt lgkmcnt(0)
	v_mov_b32_e32 v61, v56
	v_mov_b32_e32 v42, v45
	v_mov_b32_e32 v48, v47
	s_waitcnt vmcnt(1)
	v_pk_mul_f32 v[38:39], v[70:71], v[38:39]
	v_pk_mul_f32 v[40:41], v[72:73], v[40:41]
	s_waitcnt vmcnt(0)
	v_pk_mul_f32 v[58:59], v[74:75], v[58:59]
	v_cvt_pk_bf16_f32 v38, v38, v39
	v_cvt_pk_bf16_f32 v39, v40, v41
	v_cvt_pk_bf16_f32 v40, v58, v59
	v_pk_mul_f32 v[58:59], v[76:77], v[60:61]
	v_mov_b32_e32 v52, v51
	v_cvt_pk_bf16_f32 v41, v58, v59
	v_or_b32_e32 v58, s2, v16
	v_ashrrev_i32_e32 v59, 31, v58
	v_lshlrev_b64 v[58:59], 11, v[58:59]
	v_lshl_add_u64 v[58:59], v[78:79], 0, v[58:59]
	global_store_dwordx4 v[58:59], v[38:41], off
	v_mov_b32_e32 v56, v55
	ds_read2_b32 v[44:45], v21 offset0:16 offset1:24
	v_pk_mul_f32 v[38:39], v[70:71], v[42:43]
	v_pk_mul_f32 v[40:41], v[72:73], v[48:49]
	v_cvt_pk_bf16_f32 v38, v38, v39
	v_cvt_pk_bf16_f32 v39, v40, v41
	v_pk_mul_f32 v[40:41], v[74:75], v[52:53]
	v_pk_mul_f32 v[42:43], v[76:77], v[56:57]
	v_cvt_pk_bf16_f32 v40, v40, v41
	v_cvt_pk_bf16_f32 v41, v42, v43
	v_or_b32_e32 v42, s2, v18
	v_ashrrev_i32_e32 v43, 31, v42
	v_lshlrev_b64 v[42:43], 11, v[42:43]
	v_lshl_add_u64 v[42:43], v[78:79], 0, v[42:43]
	ds_read2_b32 v[46:47], v21 offset0:49 offset1:57
	global_store_dwordx4 v[42:43], v[38:41], off
	ds_read2_b32 v[42:43], v21 offset0:82 offset1:90
	ds_read2_b32 v[48:49], v21 offset0:115 offset1:123
	ds_read2_b32 v[50:51], v21 offset0:148 offset1:156
	ds_read2_b32 v[52:53], v21 offset0:181 offset1:189
	ds_read2_b32 v[54:55], v21 offset0:214 offset1:222
	ds_read2_b32 v[56:57], v21 offset0:247 offset1:255
	s_waitcnt lgkmcnt(7)
	v_mov_b32_e32 v38, v44
	s_waitcnt lgkmcnt(6)
	v_mov_b32_e32 v39, v46
	s_waitcnt lgkmcnt(5)
	v_mov_b32_e32 v40, v42
	s_waitcnt lgkmcnt(4)
	v_mov_b32_e32 v41, v48
	v_pk_mul_f32 v[38:39], v[70:71], v[38:39]
	v_pk_mul_f32 v[40:41], v[72:73], v[40:41]
	v_cvt_pk_bf16_f32 v38, v38, v39
	v_cvt_pk_bf16_f32 v39, v40, v41
	s_waitcnt lgkmcnt(3)
	v_mov_b32_e32 v40, v50
	s_waitcnt lgkmcnt(2)
	v_mov_b32_e32 v41, v52
	s_waitcnt lgkmcnt(1)
	v_mov_b32_e32 v58, v54
	s_waitcnt lgkmcnt(0)
	v_mov_b32_e32 v59, v56
	v_pk_mul_f32 v[40:41], v[74:75], v[40:41]
	v_pk_mul_f32 v[58:59], v[76:77], v[58:59]
	v_cvt_pk_bf16_f32 v40, v40, v41
	v_cvt_pk_bf16_f32 v41, v58, v59
	v_or_b32_e32 v58, s2, v19
	v_ashrrev_i32_e32 v59, 31, v58
	v_lshlrev_b64 v[58:59], 11, v[58:59]
	v_lshl_add_u64 v[58:59], v[78:79], 0, v[58:59]
	v_mov_b32_e32 v46, v45
	v_mov_b32_e32 v48, v43
	global_store_dwordx4 v[58:59], v[38:41], off
	v_mov_b32_e32 v52, v51
	v_mov_b32_e32 v56, v55
	v_pk_mul_f32 v[38:39], v[70:71], v[46:47]
	v_pk_mul_f32 v[40:41], v[72:73], v[48:49]
	v_cvt_pk_bf16_f32 v38, v38, v39
	v_cvt_pk_bf16_f32 v39, v40, v41
	v_pk_mul_f32 v[40:41], v[74:75], v[52:53]
	v_pk_mul_f32 v[42:43], v[76:77], v[56:57]
	v_cvt_pk_bf16_f32 v40, v40, v41
	v_cvt_pk_bf16_f32 v41, v42, v43
	v_or_b32_e32 v42, s2, v20
	v_ashrrev_i32_e32 v43, 31, v42
	v_lshlrev_b64 v[42:43], 11, v[42:43]
	v_lshl_add_u64 v[42:43], v[78:79], 0, v[42:43]
	global_store_dwordx4 v[42:43], v[38:41], off
	s_waitcnt lgkmcnt(0)
	s_mov_b64 s[2:3], 0
; #define GAS __attribute__((address_space(1)))
; #define LAS __attribute__((address_space(3)))
; #define LDS_WAIT() asm volatile("s_waitcnt lgkmcnt(0)" ::: "memory")
; __device__ __forceinline__ unsigned pk2(float lo, float hi) { const pkf2_t v = {lo, hi}; const pkb2_t b = __builtin_convertvector(v, pkb2_t); return __builtin_bit_cast(unsigned, b); }
; __device__ __forceinline__ void p0_transpose_item(const float* W, int K, int N, bf16* WT, int row_off, LAS float* scr, int item, int lane) {
;     const int nblk = N / 32, kb = item / nblk, nb = item % nblk, k0 = 64 * kb, n0 = 32 * nb;
;     { const int kk = lane >> 3, n4 = (lane & 7) * 4; f32x4 v[8];
; #pragma unroll
;       for (int i = 0; i < 8; ++i) v[i] = *(const GAS f32x4*)(W + (size_t)(k0 + kk + 8 * i) * N + n0 + n4);
; #pragma unroll
;       for (int i = 0; i < 8; ++i) { LAS float* d = scr + (kk + 8 * i) * 33 + n4; d[0] = v[i][0]; d[1] = v[i][1]; d[2] = v[i][2]; d[3] = v[i][3]; } }
;     LDS_WAIT(); asm volatile("" ::: "memory");
;     const int c = lane & 7;
; #pragma unroll
;     for (int j = 0; j < 4; ++j) { const int n = (lane >> 3) + 8 * j; const LAS float* s = scr + (8 * c) * 33 + n;
;         v4u o; o.x = pk2(s[0 * 33], s[1 * 33]); o.y = pk2(s[2 * 33], s[3 * 33]); o.z = pk2(s[4 * 33], s[5 * 33]); o.w = pk2(s[6 * 33], s[7 * 33]);
;         *(GAS v4u*)(WT + (size_t)(row_off + n0 + n) * K + k0 + 8 * c) = o; }
;     LDS_WAIT(); asm volatile("" ::: "memory");
.LBB0_54:
	s_andn2_b64 vcc, exec, s[2:3]
	s_cbranch_vccnz .LBB0_56
	s_and_b32 s2, s14, 0x3c0
	s_and_b32 s3, s10, 0x1e0
	v_or_b32_e32 v2, s2, v16
	s_lshl_b32 s6, s3, 2
	v_lshl_add_u64 v[38:39], v[8:9], 0, s[6:7]
	v_lshlrev_b32_e32 v2, 11, v2
	v_lshl_add_u64 v[66:67], v[38:39], 0, v[2:3]
	v_add_co_u32_e32 v42, vcc, 0x4000, v66
	v_or_b32_e32 v2, s3, v16
	s_nop 0
	v_addc_co_u32_e32 v43, vcc, 0, v67, vcc
	v_add_co_u32_e32 v46, vcc, 0x8000, v66
	global_load_dwordx4 v[38:41], v[66:67], off nt
	s_nop 0
	global_load_dwordx4 v[42:45], v[42:43], off nt
	v_addc_co_u32_e32 v47, vcc, 0, v67, vcc
	v_add_co_u32_e32 v50, vcc, 0xc000, v66
	s_lshl_b32 s6, s2, 1
	s_nop 0
	v_addc_co_u32_e32 v51, vcc, 0, v67, vcc
	s_waitcnt lgkmcnt(0)
	v_add_co_u32_e32 v54, vcc, 0x10000, v66
	global_load_dwordx4 v[46:49], v[46:47], off nt
	s_nop 0
	global_load_dwordx4 v[50:53], v[50:51], off nt
	v_addc_co_u32_e32 v55, vcc, 0, v67, vcc
	v_add_co_u32_e32 v58, vcc, 0x14000, v66
	v_or_b32_e32 v37, s3, v18
	s_nop 0
	v_addc_co_u32_e32 v59, vcc, 0, v67, vcc
	global_load_dwordx4 v[54:57], v[54:55], off nt
	s_nop 0
	global_load_dwordx4 v[58:61], v[58:59], off nt
	v_add_co_u32_e32 v62, vcc, 0x18000, v66
	v_lshl_add_u64 v[70:71], v[10:11], 0, s[6:7]
	s_nop 0
	v_addc_co_u32_e32 v63, vcc, 0, v67, vcc
	global_load_dwordx4 v[62:65], v[62:63], off nt
	v_add_co_u32_e32 v66, vcc, 0x1c000, v66
	v_lshlrev_b32_e32 v2, 11, v2
	s_nop 0
	v_addc_co_u32_e32 v67, vcc, 0, v67, vcc
	global_load_dwordx4 v[66:69], v[66:67], off nt
	v_lshl_add_u64 v[72:73], v[70:71], 0, v[2:3]
	v_lshlrev_b32_e32 v2, 11, v37
	v_lshl_add_u64 v[74:75], v[70:71], 0, v[2:3]
	v_or_b32_e32 v2, s3, v19
	v_lshlrev_b32_e32 v2, 11, v2
	s_waitcnt vmcnt(7)
	ds_write2_b32 v22, v38, v39 offset1:1
	ds_write2_b32 v22, v40, v41 offset0:2 offset1:3
	s_waitcnt vmcnt(6)
	ds_write2_b32 v23, v42, v43 offset1:1
	ds_write2_b32 v24, v44, v45 offset1:1
	s_waitcnt vmcnt(5)
	ds_write2_b32 v25, v46, v47 offset1:1
	ds_write2_b32 v26, v48, v49 offset1:1
	s_waitcnt vmcnt(4)
	ds_write2_b32 v27, v50, v51 offset1:1
	ds_write2_b32 v28, v52, v53 offset1:1
	s_waitcnt vmcnt(3)
	ds_write2_b32 v29, v54, v55 offset1:1
	ds_write2_b32 v30, v56, v57 offset1:1
	s_waitcnt vmcnt(2)
	ds_write2_b32 v31, v58, v59 offset1:1
	ds_write2_b32 v32, v60, v61 offset1:1
	s_waitcnt vmcnt(1)
	ds_write2_b32 v33, v62, v63 offset1:1
	ds_write2_b32 v34, v64, v65 offset1:1
	s_waitcnt vmcnt(0)
	ds_write2_b32 v35, v66, v67 offset1:1
	ds_write2_b32 v36, v68, v69 offset1:1
	s_waitcnt lgkmcnt(0)
	ds_read2_b32 v[42:43], v21 offset0:33 offset1:41
	ds_read2_b32 v[44:45], v21 offset1:8
	ds_read2_b32 v[46:47], v21 offset0:66 offset1:74
	ds_read2_b32 v[48:49], v21 offset0:99 offset1:107
	ds_read2_b32 v[50:51], v21 offset0:132 offset1:140
	ds_read2_b32 v[52:53], v21 offset0:165 offset1:173
	ds_read2_b32 v[54:55], v21 offset0:198 offset1:206
	ds_read2_b32 v[56:57], v21 offset0:231 offset1:239
	ds_read2_b32 v[58:59], v21 offset0:49 offset1:57
	ds_read2_b32 v[60:61], v21 offset0:16 offset1:24
	ds_read2_b32 v[62:63], v21 offset0:82 offset1:90
	ds_read2_b32 v[64:65], v21 offset0:115 offset1:123
	ds_read2_b32 v[66:67], v21 offset0:148 offset1:156
	ds_read2_b32 v[68:69], v21 offset0:181 offset1:189
	ds_read2_b32 v[76:77], v21 offset0:214 offset1:222
	ds_read2_b32 v[78:79], v21 offset0:247 offset1:255
	s_waitcnt lgkmcnt(14)
	v_cvt_pk_bf16_f32 v38, v44, v42
	s_waitcnt lgkmcnt(12)
	v_cvt_pk_bf16_f32 v39, v46, v48
	s_waitcnt lgkmcnt(10)
	v_cvt_pk_bf16_f32 v40, v50, v52
	s_waitcnt lgkmcnt(8)
	v_cvt_pk_bf16_f32 v41, v54, v56
	v_cvt_pk_bf16_f32 v42, v45, v43
	v_cvt_pk_bf16_f32 v43, v47, v49
	v_cvt_pk_bf16_f32 v44, v51, v53
	v_cvt_pk_bf16_f32 v45, v55, v57
	global_store_dwordx4 v[72:73], v[38:41], off
	global_store_dwordx4 v[74:75], v[42:45], off
	s_waitcnt lgkmcnt(6)
	v_cvt_pk_bf16_f32 v38, v60, v58
	v_lshl_add_u64 v[42:43], v[70:71], 0, v[2:3]
	v_or_b32_e32 v2, s3, v20
	s_waitcnt lgkmcnt(4)
	v_cvt_pk_bf16_f32 v39, v62, v64
	s_waitcnt lgkmcnt(2)
	v_cvt_pk_bf16_f32 v40, v66, v68
	s_waitcnt lgkmcnt(0)
	v_cvt_pk_bf16_f32 v41, v76, v78
	v_lshlrev_b32_e32 v2, 11, v2
	global_store_dwordx4 v[42:43], v[38:41], off
	v_lshl_add_u64 v[42:43], v[70:71], 0, v[2:3]
	s_nop 0
	v_cvt_pk_bf16_f32 v38, v61, v59
	v_cvt_pk_bf16_f32 v39, v63, v65
	v_cvt_pk_bf16_f32 v40, v67, v69
	v_cvt_pk_bf16_f32 v41, v77, v79
	global_store_dwordx4 v[42:43], v[38:41], off
	s_waitcnt lgkmcnt(0)

; #define GAS __attribute__((address_space(1)))
; #define LAS __attribute__((address_space(3)))
; #define LDS_WAIT() asm volatile("s_waitcnt lgkmcnt(0)" ::: "memory")
; __device__ __forceinline__ unsigned pk2(float lo, float hi) { const pkf2_t v = {lo, hi}; const pkb2_t b = __builtin_convertvector(v, pkb2_t); return __builtin_bit_cast(unsigned, b); }
; __device__ __forceinline__ void p0_transpose_item2(const float* W, int K, int N, bf16* WT, int dst_row0, const float* gain, LAS float* scr, int kb, int nb, int lane) {
;     const int k0 = 64 * kb, n0 = 32 * nb;
;     const int c = lane & 7; float gg[8];
;     { const int kk = lane >> 3, n4 = (lane & 7) * 4; f32x4 v[8];
; #pragma unroll
;       for (int i = 0; i < 8; ++i) v[i] = *(const GAS f32x4*)(W + (size_t)(k0 + kk + 8 * i) * N + n0 + n4);
; #pragma unroll
;       for (int e = 0; e < 8; ++e) gg[e] = gain[k0 + 8 * c + e];
; #pragma unroll
;       for (int i = 0; i < 8; ++i) { LAS float* d = scr + (kk + 8 * i) * 33 + n4; d[0] = v[i][0]; d[1] = v[i][1]; d[2] = v[i][2]; d[3] = v[i][3]; } }
;     LDS_WAIT(); asm volatile("" ::: "memory");
; #pragma unroll
;     for (int j = 0; j < 4; ++j) { const int n = (lane >> 3) + 8 * j; const LAS float* s = scr + (8 * c) * 33 + n;
;         v4u o; o.x = pk2(s[0 * 33] * gg[0], s[1 * 33] * gg[1]); o.y = pk2(s[2 * 33] * gg[2], s[3 * 33] * gg[3]); o.z = pk2(s[4 * 33] * gg[4], s[5 * 33] * gg[5]); o.w = pk2(s[6 * 33] * gg[6], s[7 * 33] * gg[7]);
;         *(GAS v4u*)(WT + (size_t)(dst_row0 + n) * K + k0 + 8 * c) = o; }
;     LDS_WAIT(); asm volatile("" ::: "memory");
; }
.LBB0_57:
	s_andn2_b64 vcc, exec, s[2:3]
	s_cbranch_vccnz .LBB0_50
	s_mul_hi_i32 s2, s18, 0x66666667
	s_lshr_b32 s3, s2, 31
	s_ashr_i32 s2, s2, 5
	s_add_i32 s2, s2, s3
	s_mul_i32 s3, s2, 0xfffff600
	s_add_i32 s4, s10, s3
	s_lshl_b32 s2, s2, 6
	v_or_b32_e32 v2, s2, v16
	s_ashr_i32 s5, s4, 31
	v_lshl_add_u64 v[66:67], s[4:5], 2, v[12:13]
	v_or_b32_e32 v37, 8, v2
	v_mad_i64_i32 v[42:43], s[20:21], v37, s17, v[66:67]
	v_or_b32_e32 v37, 16, v2
	v_mad_i64_i32 v[46:47], s[20:21], v37, s17, v[66:67]
	v_or_b32_e32 v37, 24, v2
	v_mad_i64_i32 v[50:51], s[20:21], v37, s17, v[66:67]
	v_or_b32_e32 v37, 32, v2
	s_waitcnt lgkmcnt(0)
	v_mad_i64_i32 v[54:55], s[20:21], v37, s17, v[66:67]
	v_or_b32_e32 v37, 40, v2
	v_mad_i64_i32 v[38:39], s[20:21], v2, s17, v[66:67]
	v_mad_i64_i32 v[58:59], s[20:21], v37, s17, v[66:67]
	global_load_dwordx4 v[38:41], v[38:39], off nt
	s_nop 0
	global_load_dwordx4 v[42:45], v[42:43], off nt
	s_nop 0
	global_load_dwordx4 v[46:49], v[46:47], off nt
	s_nop 0
	global_load_dwordx4 v[50:53], v[50:51], off nt
	s_nop 0
	global_load_dwordx4 v[54:57], v[54:55], off nt
	s_nop 0
	global_load_dwordx4 v[58:61], v[58:59], off nt
	v_or_b32_e32 v70, s2, v17
	v_readlane_b32 s48, v254, 23
	v_or_b32_e32 v37, 48, v2
	v_or_b32_e32 v2, 56, v2
	v_ashrrev_i32_e32 v71, 31, v70
	v_readlane_b32 s49, v254, 24
	v_mad_i64_i32 v[62:63], s[20:21], v37, s17, v[66:67]
	v_mad_i64_i32 v[66:67], s[20:21], v2, s17, v[66:67]
	v_lshl_add_u64 v[74:75], v[70:71], 2, s[48:49]
	global_load_dwordx4 v[62:65], v[62:63], off nt
	v_add_u32_e32 v80, s4, v16
	global_load_dwordx4 v[66:69], v[66:67], off nt
	s_nop 0
	global_load_dwordx4 v[70:73], v[74:75], off nt
	s_nop 0
	global_load_dwordx4 v[74:77], v[74:75], off offset:16 nt
	s_ashr_i32 s3, s2, 31
	v_ashrrev_i32_e32 v81, 31, v80
	v_lshl_add_u64 v[78:79], s[2:3], 1, v[14:15]
	v_lshlrev_b64 v[82:83], 11, v[80:81]
	v_lshl_add_u64 v[82:83], v[78:79], 0, v[82:83]
	v_readlane_b32 s50, v254, 25
	v_readlane_b32 s51, v254, 26
	v_readlane_b32 s52, v254, 27
	v_readlane_b32 s53, v254, 28
	v_readlane_b32 s54, v254, 29
	v_readlane_b32 s55, v254, 30
	v_readlane_b32 s56, v254, 31
	v_readlane_b32 s57, v254, 32
	v_readlane_b32 s58, v254, 33
	v_readlane_b32 s59, v254, 34
	v_readlane_b32 s60, v254, 35
	v_readlane_b32 s61, v254, 36
	v_readlane_b32 s62, v254, 37
	v_readlane_b32 s63, v254, 38
	s_waitcnt vmcnt(9)
	ds_write2_b32 v22, v38, v39 offset1:1
	ds_write2_b32 v22, v40, v41 offset0:2 offset1:3
	s_waitcnt vmcnt(8)
	ds_write2_b32 v23, v42, v43 offset1:1
	ds_write2_b32 v24, v44, v45 offset1:1
	s_waitcnt vmcnt(7)
	ds_write2_b32 v25, v46, v47 offset1:1
	ds_write2_b32 v26, v48, v49 offset1:1
	s_waitcnt vmcnt(6)
	ds_write2_b32 v27, v50, v51 offset1:1
	ds_write2_b32 v28, v52, v53 offset1:1
	s_waitcnt vmcnt(5)
	ds_write2_b32 v29, v54, v55 offset1:1
	ds_write2_b32 v30, v56, v57 offset1:1
	s_waitcnt vmcnt(4)
	ds_write2_b32 v31, v58, v59 offset1:1
	ds_write2_b32 v32, v60, v61 offset1:1
	s_waitcnt vmcnt(3)
	ds_write2_b32 v33, v62, v63 offset1:1
	ds_write2_b32 v34, v64, v65 offset1:1
	s_waitcnt vmcnt(2)
	ds_write2_b32 v35, v66, v67 offset1:1
	ds_write2_b32 v36, v68, v69 offset1:1
	s_waitcnt lgkmcnt(0)
	ds_read2_b32 v[38:39], v21 offset0:33 offset1:41
	ds_read2_b32 v[40:41], v21 offset1:8
	ds_read2_b32 v[42:43], v21 offset0:66 offset1:74
	ds_read2_b32 v[44:45], v21 offset0:99 offset1:107
	ds_read2_b32 v[46:47], v21 offset0:132 offset1:140
	ds_read2_b32 v[48:49], v21 offset0:165 offset1:173
	ds_read2_b32 v[50:51], v21 offset0:198 offset1:206
	ds_read2_b32 v[52:53], v21 offset0:231 offset1:239
	s_waitcnt lgkmcnt(6)
	v_mov_b32_e32 v54, v40
	v_mov_b32_e32 v55, v38
	s_waitcnt lgkmcnt(5)
	v_mov_b32_e32 v56, v42
	s_waitcnt lgkmcnt(4)
	v_mov_b32_e32 v57, v44
	s_waitcnt lgkmcnt(3)
	v_mov_b32_e32 v58, v46
	s_waitcnt lgkmcnt(2)
	v_mov_b32_e32 v59, v48
	s_waitcnt lgkmcnt(1)
	v_mov_b32_e32 v60, v50
	s_waitcnt lgkmcnt(0)
	v_mov_b32_e32 v61, v52
	v_mov_b32_e32 v38, v41
	v_mov_b32_e32 v44, v43
	s_waitcnt vmcnt(1)
	v_pk_mul_f32 v[40:41], v[70:71], v[54:55]
	v_pk_mul_f32 v[42:43], v[72:73], v[56:57]
	s_waitcnt vmcnt(0)
	v_pk_mul_f32 v[54:55], v[74:75], v[58:59]
	v_pk_mul_f32 v[56:57], v[76:77], v[60:61]
	v_pk_mul_f32 v[58:59], v[70:71], v[38:39]
	v_cvt_pk_bf16_f32 v38, v40, v41
	v_cvt_pk_bf16_f32 v39, v42, v43
	v_cvt_pk_bf16_f32 v40, v54, v55
	v_cvt_pk_bf16_f32 v41, v56, v57
	v_mov_b32_e32 v48, v47
	v_pk_mul_f32 v[44:45], v[72:73], v[44:45]
	global_store_dwordx4 v[82:83], v[38:41], off
	v_mov_b32_e32 v52, v51
	v_cvt_pk_bf16_f32 v43, v44, v45
	v_pk_mul_f32 v[38:39], v[74:75], v[48:49]
	v_cvt_pk_bf16_f32 v42, v58, v59
	v_cvt_pk_bf16_f32 v44, v38, v39
	v_pk_mul_f32 v[38:39], v[76:77], v[52:53]
	ds_read2_b32 v[46:47], v21 offset0:16 offset1:24
	v_cvt_pk_bf16_f32 v45, v38, v39
	v_add_u32_e32 v38, 8, v80
	v_ashrrev_i32_e32 v39, 31, v38
	v_lshlrev_b64 v[38:39], 11, v[38:39]
	v_lshl_add_u64 v[38:39], v[78:79], 0, v[38:39]
	ds_read2_b32 v[48:49], v21 offset0:49 offset1:57
	global_store_dwordx4 v[38:39], v[42:45], off
	ds_read2_b32 v[42:43], v21 offset0:82 offset1:90
	ds_read2_b32 v[44:45], v21 offset0:115 offset1:123
	ds_read2_b32 v[50:51], v21 offset0:148 offset1:156
	ds_read2_b32 v[52:53], v21 offset0:181 offset1:189
	ds_read2_b32 v[54:55], v21 offset0:214 offset1:222
	ds_read2_b32 v[56:57], v21 offset0:247 offset1:255
	s_waitcnt lgkmcnt(7)
	v_mov_b32_e32 v38, v46
	s_waitcnt lgkmcnt(6)
	v_mov_b32_e32 v39, v48
	s_waitcnt lgkmcnt(5)
	v_mov_b32_e32 v40, v42
	s_waitcnt lgkmcnt(4)
	v_mov_b32_e32 v41, v44
	v_pk_mul_f32 v[38:39], v[70:71], v[38:39]
	v_pk_mul_f32 v[40:41], v[72:73], v[40:41]
	v_cvt_pk_bf16_f32 v38, v38, v39
	v_cvt_pk_bf16_f32 v39, v40, v41
	s_waitcnt lgkmcnt(3)
	v_mov_b32_e32 v40, v50
	s_waitcnt lgkmcnt(2)
	v_mov_b32_e32 v41, v52
	s_waitcnt lgkmcnt(1)
	v_mov_b32_e32 v58, v54
	s_waitcnt lgkmcnt(0)
	v_mov_b32_e32 v59, v56
	v_pk_mul_f32 v[40:41], v[74:75], v[40:41]
	v_pk_mul_f32 v[58:59], v[76:77], v[58:59]
	v_cvt_pk_bf16_f32 v40, v40, v41
	v_cvt_pk_bf16_f32 v41, v58, v59
	v_add_u32_e32 v58, 16, v80
	v_ashrrev_i32_e32 v59, 31, v58
	v_lshlrev_b64 v[58:59], 11, v[58:59]
	v_lshl_add_u64 v[58:59], v[78:79], 0, v[58:59]
	v_mov_b32_e32 v48, v47
	v_mov_b32_e32 v44, v43
	global_store_dwordx4 v[58:59], v[38:41], off
	v_mov_b32_e32 v52, v51
	v_mov_b32_e32 v56, v55
	v_pk_mul_f32 v[38:39], v[70:71], v[48:49]
	v_pk_mul_f32 v[40:41], v[72:73], v[44:45]
	v_cvt_pk_bf16_f32 v38, v38, v39
	v_cvt_pk_bf16_f32 v39, v40, v41
	v_pk_mul_f32 v[40:41], v[74:75], v[52:53]
	v_pk_mul_f32 v[42:43], v[76:77], v[56:57]
	v_cvt_pk_bf16_f32 v40, v40, v41
	v_cvt_pk_bf16_f32 v41, v42, v43
	v_add_u32_e32 v42, 24, v80
	v_ashrrev_i32_e32 v43, 31, v42
	v_lshlrev_b64 v[42:43], 11, v[42:43]
	v_lshl_add_u64 v[42:43], v[78:79], 0, v[42:43]
	global_store_dwordx4 v[42:43], v[38:41], off
	s_waitcnt lgkmcnt(0)
	s_branch .LBB0_50

; #define GAS __attribute__((address_space(1)))
; #define LAS __attribute__((address_space(3)))
; #define LDS_WAIT() asm volatile("s_waitcnt lgkmcnt(0)" ::: "memory")
; __device__ __forceinline__ unsigned pk2(float lo, float hi) { const pkf2_t v = {lo, hi}; const pkb2_t b = __builtin_convertvector(v, pkb2_t); return __builtin_bit_cast(unsigned, b); }
; __device__ __forceinline__ void p0_transpose_item(const float* W, int K, int N, bf16* WT, int row_off, LAS float* scr, int item, int lane) {
;     const int nblk = N / 32, kb = item / nblk, nb = item % nblk, k0 = 64 * kb, n0 = 32 * nb;
;     { const int kk = lane >> 3, n4 = (lane & 7) * 4; f32x4 v[8];
; #pragma unroll
;       for (int i = 0; i < 8; ++i) v[i] = *(const GAS f32x4*)(W + (size_t)(k0 + kk + 8 * i) * N + n0 + n4);
; #pragma unroll
;       for (int i = 0; i < 8; ++i) { LAS float* d = scr + (kk + 8 * i) * 33 + n4; d[0] = v[i][0]; d[1] = v[i][1]; d[2] = v[i][2]; d[3] = v[i][3]; } }
;     LDS_WAIT(); asm volatile("" ::: "memory");
;     const int c = lane & 7;
; #pragma unroll
;     for (int j = 0; j < 4; ++j) { const int n = (lane >> 3) + 8 * j; const LAS float* s = scr + (8 * c) * 33 + n;
;         v4u o; o.x = pk2(s[0 * 33], s[1 * 33]); o.y = pk2(s[2 * 33], s[3 * 33]); o.z = pk2(s[4 * 33], s[5 * 33]); o.w = pk2(s[6 * 33], s[7 * 33]);
;         *(GAS v4u*)(WT + (size_t)(row_off + n0 + n) * K + k0 + 8 * c) = o; }
;     LDS_WAIT(); asm volatile("" ::: "memory");
.LBB0_62:
	s_cmpk_gt_i32 s9, 0x1ff
	s_mov_b64 s[2:3], -1
	s_cbranch_scc0 .LBB0_64
	s_add_i32 s0, s5, 0x1fc00
	s_and_b32 s2, s0, 0x1ffc0
	s_and_b32 s3, s7, 0x3e0
	v_or_b32_e32 v2, s2, v12
	s_lshl_b32 s0, s3, 2
	v_lshl_add_u64 v[32:33], v[4:5], 0, s[0:1]
	v_lshlrev_b32_e32 v2, 12, v2
	v_lshl_add_u64 v[60:61], v[32:33], 0, v[2:3]
	v_add_co_u32_e32 v36, vcc, 0x8000, v60
	v_or_b32_e32 v2, s3, v12
	s_nop 0
	v_addc_co_u32_e32 v37, vcc, 0, v61, vcc
	v_add_co_u32_e32 v40, vcc, 0x10000, v60
	global_load_dwordx4 v[32:35], v[60:61], off nt
	s_nop 0
	global_load_dwordx4 v[36:39], v[36:37], off nt
	v_addc_co_u32_e32 v41, vcc, 0, v61, vcc
	v_add_co_u32_e32 v44, vcc, 0x18000, v60
	s_lshl_b32 s0, s2, 1
	s_nop 0
	v_addc_co_u32_e32 v45, vcc, 0, v61, vcc
	v_add_co_u32_e32 v48, vcc, 0x20000, v60
	global_load_dwordx4 v[40:43], v[40:41], off nt
	s_nop 0
	global_load_dwordx4 v[44:47], v[44:45], off nt
	v_addc_co_u32_e32 v49, vcc, 0, v61, vcc
	v_add_co_u32_e32 v52, vcc, 0x28000, v60
	v_or_b32_e32 v68, s3, v13
	s_nop 0
	v_addc_co_u32_e32 v53, vcc, 0, v61, vcc
	global_load_dwordx4 v[48:51], v[48:49], off nt
	s_waitcnt lgkmcnt(0)
	global_load_dwordx4 v[52:55], v[52:53], off nt
	v_add_co_u32_e32 v56, vcc, 0x30000, v60
	v_lshl_add_u64 v[64:65], v[6:7], 0, s[0:1]
	s_nop 0
	v_addc_co_u32_e32 v57, vcc, 0, v61, vcc
	global_load_dwordx4 v[56:59], v[56:57], off nt
	v_add_co_u32_e32 v60, vcc, 0x38000, v60
	v_mul_u32_u24_e32 v2, 0x1600, v2
	s_nop 0
	v_addc_co_u32_e32 v61, vcc, 0, v61, vcc
	global_load_dwordx4 v[60:63], v[60:61], off nt
	v_lshl_add_u64 v[66:67], v[64:65], 0, v[2:3]
	v_mul_u32_u24_e32 v2, 0x1600, v68
	v_lshl_add_u64 v[68:69], v[64:65], 0, v[2:3]
	v_or_b32_e32 v2, s3, v14
	v_mul_u32_u24_e32 v2, 0x1600, v2
	s_waitcnt vmcnt(7)
	ds_write2_b32 v17, v32, v33 offset1:1
	ds_write2_b32 v17, v34, v35 offset0:2 offset1:3
	s_waitcnt vmcnt(6)
	ds_write2_b32 v18, v36, v37 offset1:1
	ds_write2_b32 v19, v38, v39 offset1:1
	s_waitcnt vmcnt(5)
	ds_write2_b32 v20, v40, v41 offset1:1
	ds_write2_b32 v21, v42, v43 offset1:1
	s_waitcnt vmcnt(4)
	ds_write2_b32 v22, v44, v45 offset1:1
	ds_write2_b32 v23, v46, v47 offset1:1
	s_waitcnt vmcnt(3)
	ds_write2_b32 v24, v48, v49 offset1:1
	ds_write2_b32 v25, v50, v51 offset1:1
	s_waitcnt vmcnt(2)
	ds_write2_b32 v26, v52, v53 offset1:1
	ds_write2_b32 v27, v54, v55 offset1:1
	s_waitcnt vmcnt(1)
	ds_write2_b32 v28, v56, v57 offset1:1
	ds_write2_b32 v29, v58, v59 offset1:1
	s_waitcnt vmcnt(0)
	ds_write2_b32 v30, v60, v61 offset1:1
	ds_write2_b32 v31, v62, v63 offset1:1
	s_waitcnt lgkmcnt(0)
	ds_read2_b32 v[36:37], v16 offset0:33 offset1:41
	ds_read2_b32 v[38:39], v16 offset1:8
	ds_read2_b32 v[40:41], v16 offset0:66 offset1:74
	ds_read2_b32 v[42:43], v16 offset0:99 offset1:107
	ds_read2_b32 v[44:45], v16 offset0:132 offset1:140
	ds_read2_b32 v[46:47], v16 offset0:165 offset1:173
	ds_read2_b32 v[48:49], v16 offset0:198 offset1:206
	ds_read2_b32 v[50:51], v16 offset0:231 offset1:239
	ds_read2_b32 v[52:53], v16 offset0:16 offset1:24
	ds_read2_b32 v[54:55], v16 offset0:49 offset1:57
	ds_read2_b32 v[56:57], v16 offset0:82 offset1:90
	ds_read2_b32 v[58:59], v16 offset0:115 offset1:123
	ds_read2_b32 v[60:61], v16 offset0:148 offset1:156
	ds_read2_b32 v[62:63], v16 offset0:181 offset1:189
	ds_read2_b32 v[70:71], v16 offset0:214 offset1:222
	ds_read2_b32 v[72:73], v16 offset0:247 offset1:255
	s_waitcnt lgkmcnt(14)
	v_cvt_pk_bf16_f32 v32, v38, v36
	s_waitcnt lgkmcnt(12)
	v_cvt_pk_bf16_f32 v33, v40, v42
	s_waitcnt lgkmcnt(10)
	v_cvt_pk_bf16_f32 v34, v44, v46
	s_waitcnt lgkmcnt(8)
	v_cvt_pk_bf16_f32 v35, v48, v50
	v_cvt_pk_bf16_f32 v36, v39, v37
	v_cvt_pk_bf16_f32 v37, v41, v43
	v_cvt_pk_bf16_f32 v38, v45, v47
	v_cvt_pk_bf16_f32 v39, v49, v51
	global_store_dwordx4 v[66:67], v[32:35], off
	global_store_dwordx4 v[68:69], v[36:39], off
	s_waitcnt lgkmcnt(6)
	v_cvt_pk_bf16_f32 v32, v52, v54
	v_lshl_add_u64 v[36:37], v[64:65], 0, v[2:3]
	v_or_b32_e32 v2, s3, v15
	s_waitcnt lgkmcnt(4)
	v_cvt_pk_bf16_f32 v33, v56, v58
	s_waitcnt lgkmcnt(2)
	v_cvt_pk_bf16_f32 v34, v60, v62
	s_waitcnt lgkmcnt(0)
	v_cvt_pk_bf16_f32 v35, v70, v72
	v_mul_u32_u24_e32 v2, 0x1600, v2
	global_store_dwordx4 v[36:37], v[32:35], off
	v_lshl_add_u64 v[36:37], v[64:65], 0, v[2:3]
	s_mov_b64 s[2:3], 0
	v_cvt_pk_bf16_f32 v32, v53, v55
	v_cvt_pk_bf16_f32 v33, v57, v59
	v_cvt_pk_bf16_f32 v34, v61, v63
	v_cvt_pk_bf16_f32 v35, v71, v73
	global_store_dwordx4 v[36:37], v[32:35], off
	s_waitcnt lgkmcnt(0)
; #define GAS __attribute__((address_space(1)))
; #define LAS __attribute__((address_space(3)))
; #define LDS_WAIT() asm volatile("s_waitcnt lgkmcnt(0)" ::: "memory")
; __device__ __forceinline__ unsigned pk2(float lo, float hi) { const pkf2_t v = {lo, hi}; const pkb2_t b = __builtin_convertvector(v, pkb2_t); return __builtin_bit_cast(unsigned, b); }
; __device__ __forceinline__ void p0_transpose_item(const float* W, int K, int N, bf16* WT, int row_off, LAS float* scr, int item, int lane) {
;     const int nblk = N / 32, kb = item / nblk, nb = item % nblk, k0 = 64 * kb, n0 = 32 * nb;
;     { const int kk = lane >> 3, n4 = (lane & 7) * 4; f32x4 v[8];
; #pragma unroll
;       for (int i = 0; i < 8; ++i) v[i] = *(const GAS f32x4*)(W + (size_t)(k0 + kk + 8 * i) * N + n0 + n4);
; #pragma unroll
;       for (int i = 0; i < 8; ++i) { LAS float* d = scr + (kk + 8 * i) * 33 + n4; d[0] = v[i][0]; d[1] = v[i][1]; d[2] = v[i][2]; d[3] = v[i][3]; } }
;     LDS_WAIT(); asm volatile("" ::: "memory");
;     const int c = lane & 7;
; #pragma unroll
;     for (int j = 0; j < 4; ++j) { const int n = (lane >> 3) + 8 * j; const LAS float* s = scr + (8 * c) * 33 + n;
;         v4u o; o.x = pk2(s[0 * 33], s[1 * 33]); o.y = pk2(s[2 * 33], s[3 * 33]); o.z = pk2(s[4 * 33], s[5 * 33]); o.w = pk2(s[6 * 33], s[7 * 33]);
;         *(GAS v4u*)(WT + (size_t)(row_off + n0 + n) * K + k0 + 8 * c) = o; }
;     LDS_WAIT(); asm volatile("" ::: "memory");
.LBB0_64:
	s_andn2_b64 vcc, exec, s[2:3]
	s_cbranch_vccnz .LBB0_61
	s_cmpk_lt_i32 s9, 0x80
	s_cbranch_scc1 .LBB0_61
	s_and_b32 s2, s5, 0x1ffc0
	s_and_b32 s3, s7, 0x3e0
	v_or_b32_e32 v2, s2, v12
	s_lshl_b32 s0, s3, 2
	v_lshl_add_u64 v[32:33], v[8:9], 0, s[0:1]
	v_lshlrev_b32_e32 v2, 12, v2
	v_lshl_add_u64 v[60:61], v[32:33], 0, v[2:3]
	v_add_co_u32_e32 v36, vcc, 0x8000, v60
	v_or_b32_e32 v2, s3, v12
	s_nop 0
	v_addc_co_u32_e32 v37, vcc, 0, v61, vcc
	v_add_co_u32_e32 v40, vcc, 0x10000, v60
	global_load_dwordx4 v[32:35], v[60:61], off nt
	s_nop 0
	global_load_dwordx4 v[36:39], v[36:37], off nt
	v_addc_co_u32_e32 v41, vcc, 0, v61, vcc
	v_add_co_u32_e32 v44, vcc, 0x18000, v60
	s_lshl_b32 s0, s2, 1
	s_nop 0
	v_addc_co_u32_e32 v45, vcc, 0, v61, vcc
	v_add_co_u32_e32 v48, vcc, 0x20000, v60
	global_load_dwordx4 v[40:43], v[40:41], off nt
	s_nop 0
	global_load_dwordx4 v[44:47], v[44:45], off nt
	v_addc_co_u32_e32 v49, vcc, 0, v61, vcc
	v_add_co_u32_e32 v52, vcc, 0x28000, v60
	v_or_b32_e32 v68, s3, v13
	s_nop 0
	v_addc_co_u32_e32 v53, vcc, 0, v61, vcc
	global_load_dwordx4 v[48:51], v[48:49], off nt
	s_waitcnt lgkmcnt(0)
	global_load_dwordx4 v[52:55], v[52:53], off nt
	v_add_co_u32_e32 v56, vcc, 0x30000, v60
	v_lshl_add_u64 v[64:65], v[10:11], 0, s[0:1]
	s_nop 0
	v_addc_co_u32_e32 v57, vcc, 0, v61, vcc
	global_load_dwordx4 v[56:59], v[56:57], off nt
	v_add_co_u32_e32 v60, vcc, 0x38000, v60
	v_lshlrev_b32_e32 v2, 11, v2
	s_nop 0
	v_addc_co_u32_e32 v61, vcc, 0, v61, vcc
	global_load_dwordx4 v[60:63], v[60:61], off nt
	v_lshl_add_u64 v[66:67], v[64:65], 0, v[2:3]
	v_lshlrev_b32_e32 v2, 11, v68
	v_lshl_add_u64 v[68:69], v[64:65], 0, v[2:3]
	v_or_b32_e32 v2, s3, v14
	v_lshlrev_b32_e32 v2, 11, v2
	s_waitcnt vmcnt(7)
	ds_write2_b32 v17, v32, v33 offset1:1
	ds_write2_b32 v17, v34, v35 offset0:2 offset1:3
	s_waitcnt vmcnt(6)
	ds_write2_b32 v18, v36, v37 offset1:1
	ds_write2_b32 v19, v38, v39 offset1:1
	s_waitcnt vmcnt(5)
	ds_write2_b32 v20, v40, v41 offset1:1
	ds_write2_b32 v21, v42, v43 offset1:1
	s_waitcnt vmcnt(4)
	ds_write2_b32 v22, v44, v45 offset1:1
	ds_write2_b32 v23, v46, v47 offset1:1
	s_waitcnt vmcnt(3)
	ds_write2_b32 v24, v48, v49 offset1:1
	ds_write2_b32 v25, v50, v51 offset1:1
	s_waitcnt vmcnt(2)
	ds_write2_b32 v26, v52, v53 offset1:1
	ds_write2_b32 v27, v54, v55 offset1:1
	s_waitcnt vmcnt(1)
	ds_write2_b32 v28, v56, v57 offset1:1
	ds_write2_b32 v29, v58, v59 offset1:1
	s_waitcnt vmcnt(0)
	ds_write2_b32 v30, v60, v61 offset1:1
	ds_write2_b32 v31, v62, v63 offset1:1
	s_waitcnt lgkmcnt(0)
	ds_read2_b32 v[36:37], v16 offset0:33 offset1:41
	ds_read2_b32 v[38:39], v16 offset1:8
	ds_read2_b32 v[40:41], v16 offset0:66 offset1:74
	ds_read2_b32 v[42:43], v16 offset0:99 offset1:107
	ds_read2_b32 v[44:45], v16 offset0:132 offset1:140
	ds_read2_b32 v[46:47], v16 offset0:165 offset1:173
	ds_read2_b32 v[48:49], v16 offset0:198 offset1:206
	ds_read2_b32 v[50:51], v16 offset0:231 offset1:239
	ds_read2_b32 v[52:53], v16 offset0:49 offset1:57
	ds_read2_b32 v[54:55], v16 offset0:16 offset1:24
	ds_read2_b32 v[56:57], v16 offset0:82 offset1:90
	ds_read2_b32 v[58:59], v16 offset0:115 offset1:123
	ds_read2_b32 v[60:61], v16 offset0:148 offset1:156
	ds_read2_b32 v[62:63], v16 offset0:181 offset1:189
	ds_read2_b32 v[70:71], v16 offset0:214 offset1:222
	ds_read2_b32 v[72:73], v16 offset0:247 offset1:255
	s_waitcnt lgkmcnt(14)
	v_cvt_pk_bf16_f32 v32, v38, v36
	s_waitcnt lgkmcnt(12)
	v_cvt_pk_bf16_f32 v33, v40, v42
	s_waitcnt lgkmcnt(10)
	v_cvt_pk_bf16_f32 v34, v44, v46
	s_waitcnt lgkmcnt(8)
	v_cvt_pk_bf16_f32 v35, v48, v50
	v_cvt_pk_bf16_f32 v36, v39, v37
	v_cvt_pk_bf16_f32 v37, v41, v43
	v_cvt_pk_bf16_f32 v38, v45, v47
	v_cvt_pk_bf16_f32 v39, v49, v51
	global_store_dwordx4 v[66:67], v[32:35], off
	global_store_dwordx4 v[68:69], v[36:39], off
	s_waitcnt lgkmcnt(6)
	v_cvt_pk_bf16_f32 v32, v54, v52
	v_lshl_add_u64 v[36:37], v[64:65], 0, v[2:3]
	v_or_b32_e32 v2, s3, v15
	s_waitcnt lgkmcnt(4)
	v_cvt_pk_bf16_f32 v33, v56, v58
	s_waitcnt lgkmcnt(2)
	v_cvt_pk_bf16_f32 v34, v60, v62
	s_waitcnt lgkmcnt(0)
	v_cvt_pk_bf16_f32 v35, v70, v72
	v_lshlrev_b32_e32 v2, 11, v2
	global_store_dwordx4 v[36:37], v[32:35], off
	v_lshl_add_u64 v[36:37], v[64:65], 0, v[2:3]
	s_nop 0
	v_cvt_pk_bf16_f32 v32, v55, v53
	v_cvt_pk_bf16_f32 v33, v57, v59
	v_cvt_pk_bf16_f32 v34, v61, v63
	v_cvt_pk_bf16_f32 v35, v71, v73
	global_store_dwordx4 v[36:37], v[32:35], off
	s_waitcnt lgkmcnt(0)
	s_branch .LBB0_61

; #define GAS __attribute__((address_space(1)))
; #define LAS __attribute__((address_space(3)))
; #define LDS_WAIT() asm volatile("s_waitcnt lgkmcnt(0)" ::: "memory")
; __device__ __forceinline__ unsigned pk2(float lo, float hi) { const pkf2_t v = {lo, hi}; const pkb2_t b = __builtin_convertvector(v, pkb2_t); return __builtin_bit_cast(unsigned, b); }
; __device__ __forceinline__ void p0_transpose_item2(const float* W, int K, int N, bf16* WT, int dst_row0, const float* gain, LAS float* scr, int kb, int nb, int lane) {
;     const int k0 = 64 * kb, n0 = 32 * nb;
;     const int c = lane & 7; float gg[8];
;     { const int kk = lane >> 3, n4 = (lane & 7) * 4; f32x4 v[8];
; #pragma unroll
;       for (int i = 0; i < 8; ++i) v[i] = *(const GAS f32x4*)(W + (size_t)(k0 + kk + 8 * i) * N + n0 + n4);
; #pragma unroll
;       for (int e = 0; e < 8; ++e) gg[e] = gain[k0 + 8 * c + e];
; #pragma unroll
;       for (int i = 0; i < 8; ++i) { LAS float* d = scr + (kk + 8 * i) * 33 + n4; d[0] = v[i][0]; d[1] = v[i][1]; d[2] = v[i][2]; d[3] = v[i][3]; } }
;     LDS_WAIT(); asm volatile("" ::: "memory");
; #pragma unroll
;     for (int j = 0; j < 4; ++j) { const int n = (lane >> 3) + 8 * j; const LAS float* s = scr + (8 * c) * 33 + n;
;         v4u o; o.x = pk2(s[0 * 33] * gg[0], s[1 * 33] * gg[1]); o.y = pk2(s[2 * 33] * gg[2], s[3 * 33] * gg[3]); o.z = pk2(s[4 * 33] * gg[4], s[5 * 33] * gg[5]); o.w = pk2(s[6 * 33] * gg[6], s[7 * 33] * gg[7]);
;         *(GAS v4u*)(WT + (size_t)(dst_row0 + n) * K + k0 + 8 * c) = o; }
;     LDS_WAIT(); asm volatile("" ::: "memory");
; }
; __device__ __forceinline__ void p0_wup_item(Frame& F, LAS float* scr, int r) {
;     const int nblk = 2 * DFF / 32, kb = r / nblk, nb = r % nblk, n0 = 32 * nb, j = n0 < DFF ? n0 : n0 - DFF;
;     p0_transpose_item2(F.w_up, D, 2 * DFF, F.WUP, (j >> 7) * 256 + (j & 127) + (n0 < DFF ? 0 : 128), F.ln2_g, scr, kb, nb, F.lane);
.LBB0_75:
	s_cmpk_gt_i32 s23, 0x4ff
	s_mov_b64 s[2:3], -1
	s_cbranch_scc0 .LBB0_81
	s_cmpk_gt_u32 s23, 0x5ff
	s_cbranch_scc0 .LBB0_78
	s_add_i32 s2, s23, 0xfa00
	s_and_b32 s3, s2, 0xffff
	s_mul_i32 s3, s3, 0xba2f
	s_lshr_b32 s3, s3, 23
	s_mul_i32 s4, s3, 0xb0
	s_sub_i32 s2, s2, s4
	s_lshl_b32 s4, s2, 5
	s_and_b32 s4, s4, 0xffe0
	s_and_b32 s2, s2, 0xffff
	s_add_i32 s5, s4, 0xfffff500
	s_cmpk_lt_u32 s2, 0x58
	s_cselect_b32 s2, s4, s5
	s_cselect_b32 s5, 0, 0x80
	s_lshl_b32 s24, s3, 6
	v_or_b32_e32 v2, s24, v16
	s_lshl_b32 s14, s4, 2
	v_lshl_add_u64 v[38:39], v[4:5], 0, s[14:15]
	v_mul_u32_u24_e32 v2, 0x5800, v2
	v_lshl_add_u64 v[66:67], v[38:39], 0, v[2:3]
	s_mov_b32 s4, 0x2c000
	v_add_co_u32_e32 v42, vcc, s4, v66
	s_mov_b32 s4, 0x58000
	s_nop 0
	v_addc_co_u32_e32 v43, vcc, 0, v67, vcc
	v_add_co_u32_e32 v46, vcc, s4, v66
	global_load_dwordx4 v[38:41], v[66:67], off nt
	s_nop 0
	global_load_dwordx4 v[42:45], v[42:43], off nt
	v_addc_co_u32_e32 v47, vcc, 0, v67, vcc
	v_add_co_u32_e32 v50, vcc, s17, v66
	v_or_b32_e32 v2, s24, v17
	s_nop 0
	v_addc_co_u32_e32 v51, vcc, 0, v67, vcc
	s_waitcnt lgkmcnt(0)
	v_add_co_u32_e32 v54, vcc, s18, v66
	global_load_dwordx4 v[46:49], v[46:47], off nt
	s_nop 0
	global_load_dwordx4 v[50:53], v[50:51], off nt
	v_addc_co_u32_e32 v55, vcc, 0, v67, vcc
	v_add_co_u32_e32 v58, vcc, s19, v66
	v_lshlrev_b32_e32 v2, 2, v2
	s_nop 0
	v_addc_co_u32_e32 v59, vcc, 0, v67, vcc
	global_load_dwordx4 v[54:57], v[54:55], off nt
	s_nop 0
	global_load_dwordx4 v[58:61], v[58:59], off nt
	v_add_co_u32_e32 v62, vcc, s20, v66
	s_lshl_b32 s4, s2, 1
	s_nop 0
	v_addc_co_u32_e32 v63, vcc, 0, v67, vcc
	v_add_co_u32_e32 v66, vcc, s21, v66
	global_load_dwordx4 v[62:65], v[62:63], off nt
	s_nop 0
	v_addc_co_u32_e32 v67, vcc, 0, v67, vcc
	global_load_dwordx4 v[66:69], v[66:67], off nt
	s_nop 0
	global_load_dwordx4 v[70:73], v2, s[38:39] nt
	global_load_dwordx4 v[74:77], v2, s[38:39] offset:16 nt
	s_and_b32 s2, s2, 0x60
	s_lshl_b32 s14, s3, 7
	s_and_b32 s3, s4, 0xffffff00
	s_or_b32 s2, s2, s5
	s_or_b32 s2, s2, s3
	v_lshl_add_u64 v[78:79], v[6:7], 0, s[14:15]
	s_waitcnt vmcnt(9)
	ds_write2_b32 v22, v38, v39 offset1:1
	ds_write2_b32 v22, v40, v41 offset0:2 offset1:3
	s_waitcnt vmcnt(8)
	ds_write2_b32 v23, v42, v43 offset1:1
	ds_write2_b32 v24, v44, v45 offset1:1
	s_waitcnt vmcnt(7)
	ds_write2_b32 v25, v46, v47 offset1:1
	ds_write2_b32 v26, v48, v49 offset1:1
	s_waitcnt vmcnt(6)
	ds_write2_b32 v27, v50, v51 offset1:1
	ds_write2_b32 v28, v52, v53 offset1:1
	s_waitcnt vmcnt(5)
	ds_write2_b32 v29, v54, v55 offset1:1
	ds_write2_b32 v30, v56, v57 offset1:1
	s_waitcnt vmcnt(4)
	ds_write2_b32 v31, v58, v59 offset1:1
	ds_write2_b32 v32, v60, v61 offset1:1
	s_waitcnt vmcnt(3)
	ds_write2_b32 v33, v62, v63 offset1:1
	ds_write2_b32 v34, v64, v65 offset1:1
	s_waitcnt vmcnt(2)
	ds_write2_b32 v35, v66, v67 offset1:1
	ds_write2_b32 v36, v68, v69 offset1:1
	s_waitcnt lgkmcnt(0)
	ds_read2_b32 v[42:43], v21 offset0:33 offset1:41
	ds_read2_b32 v[44:45], v21 offset1:8
	ds_read2_b32 v[46:47], v21 offset0:66 offset1:74
	ds_read2_b32 v[48:49], v21 offset0:99 offset1:107
	ds_read2_b32 v[50:51], v21 offset0:132 offset1:140
	ds_read2_b32 v[52:53], v21 offset0:165 offset1:173
	ds_read2_b32 v[54:55], v21 offset0:198 offset1:206
	ds_read2_b32 v[56:57], v21 offset0:231 offset1:239
	s_waitcnt lgkmcnt(6)
	v_mov_b32_e32 v38, v44
	v_mov_b32_e32 v39, v42
	s_waitcnt lgkmcnt(5)
	v_mov_b32_e32 v40, v46
	s_waitcnt lgkmcnt(4)
	v_mov_b32_e32 v41, v48
	s_waitcnt lgkmcnt(3)
	v_mov_b32_e32 v58, v50
	s_waitcnt lgkmcnt(2)
	v_mov_b32_e32 v59, v52
	s_waitcnt lgkmcnt(1)
	v_mov_b32_e32 v60, v54
	s_waitcnt lgkmcnt(0)
	v_mov_b32_e32 v61, v56
	s_waitcnt vmcnt(1)
	v_pk_mul_f32 v[38:39], v[70:71], v[38:39]
	v_pk_mul_f32 v[40:41], v[72:73], v[40:41]
	s_waitcnt vmcnt(0)
	v_pk_mul_f32 v[58:59], v[74:75], v[58:59]
	v_cvt_pk_bf16_f32 v38, v38, v39
	v_cvt_pk_bf16_f32 v39, v40, v41
	v_cvt_pk_bf16_f32 v40, v58, v59
	v_pk_mul_f32 v[58:59], v[76:77], v[60:61]
	v_mov_b32_e32 v42, v45
	v_cvt_pk_bf16_f32 v41, v58, v59
	v_or_b32_e32 v58, s2, v16
	v_ashrrev_i32_e32 v59, 31, v58
	v_lshlrev_b64 v[58:59], 11, v[58:59]
	v_lshl_add_u64 v[58:59], v[78:79], 0, v[58:59]
	v_mov_b32_e32 v48, v47
	global_store_dwordx4 v[58:59], v[38:41], off
	v_mov_b32_e32 v52, v51
	v_mov_b32_e32 v56, v55
	v_pk_mul_f32 v[38:39], v[70:71], v[42:43]
	v_pk_mul_f32 v[40:41], v[72:73], v[48:49]
	v_cvt_pk_bf16_f32 v38, v38, v39
	v_cvt_pk_bf16_f32 v39, v40, v41
	v_pk_mul_f32 v[40:41], v[74:75], v[52:53]
	v_pk_mul_f32 v[42:43], v[76:77], v[56:57]
	v_cvt_pk_bf16_f32 v40, v40, v41
	v_cvt_pk_bf16_f32 v41, v42, v43
	v_or_b32_e32 v42, s2, v18
	v_ashrrev_i32_e32 v43, 31, v42
	v_lshlrev_b64 v[42:43], 11, v[42:43]
	v_lshl_add_u64 v[42:43], v[78:79], 0, v[42:43]
	ds_read2_b32 v[44:45], v21 offset0:16 offset1:24
	ds_read2_b32 v[46:47], v21 offset0:49 offset1:57
	global_store_dwordx4 v[42:43], v[38:41], off
	ds_read2_b32 v[42:43], v21 offset0:82 offset1:90
	ds_read2_b32 v[48:49], v21 offset0:115 offset1:123
	ds_read2_b32 v[50:51], v21 offset0:148 offset1:156
	ds_read2_b32 v[52:53], v21 offset0:181 offset1:189
	ds_read2_b32 v[54:55], v21 offset0:214 offset1:222
	ds_read2_b32 v[56:57], v21 offset0:247 offset1:255
	s_waitcnt lgkmcnt(7)
	v_mov_b32_e32 v38, v44
	s_waitcnt lgkmcnt(6)
	v_mov_b32_e32 v39, v46
	s_waitcnt lgkmcnt(5)
	v_mov_b32_e32 v40, v42
	s_waitcnt lgkmcnt(4)
	v_mov_b32_e32 v41, v48
	v_pk_mul_f32 v[38:39], v[70:71], v[38:39]
	v_pk_mul_f32 v[40:41], v[72:73], v[40:41]
	v_cvt_pk_bf16_f32 v38, v38, v39
	v_cvt_pk_bf16_f32 v39, v40, v41
	s_waitcnt lgkmcnt(3)
	v_mov_b32_e32 v40, v50
	s_waitcnt lgkmcnt(2)
	v_mov_b32_e32 v41, v52
	s_waitcnt lgkmcnt(1)
	v_mov_b32_e32 v58, v54
	s_waitcnt lgkmcnt(0)
	v_mov_b32_e32 v59, v56
	v_pk_mul_f32 v[40:41], v[74:75], v[40:41]
	v_pk_mul_f32 v[58:59], v[76:77], v[58:59]
	v_cvt_pk_bf16_f32 v40, v40, v41
	v_cvt_pk_bf16_f32 v41, v58, v59
	v_or_b32_e32 v58, s2, v19
	v_ashrrev_i32_e32 v59, 31, v58
	v_lshlrev_b64 v[58:59], 11, v[58:59]
	v_lshl_add_u64 v[58:59], v[78:79], 0, v[58:59]
	v_mov_b32_e32 v46, v45
	v_mov_b32_e32 v48, v43
	global_store_dwordx4 v[58:59], v[38:41], off
	v_mov_b32_e32 v52, v51
	v_mov_b32_e32 v56, v55
	v_pk_mul_f32 v[38:39], v[70:71], v[46:47]
	v_pk_mul_f32 v[40:41], v[72:73], v[48:49]
	v_cvt_pk_bf16_f32 v38, v38, v39
	v_cvt_pk_bf16_f32 v39, v40, v41
	v_pk_mul_f32 v[40:41], v[74:75], v[52:53]
	v_pk_mul_f32 v[42:43], v[76:77], v[56:57]
	v_cvt_pk_bf16_f32 v40, v40, v41
	v_cvt_pk_bf16_f32 v41, v42, v43
	v_or_b32_e32 v42, s2, v20
	v_ashrrev_i32_e32 v43, 31, v42
	v_lshlrev_b64 v[42:43], 11, v[42:43]
	v_lshl_add_u64 v[42:43], v[78:79], 0, v[42:43]
	global_store_dwordx4 v[42:43], v[38:41], off
	s_waitcnt lgkmcnt(0)
	s_mov_b64 s[2:3], 0
; #define GAS __attribute__((address_space(1)))
; #define LAS __attribute__((address_space(3)))
; #define LDS_WAIT() asm volatile("s_waitcnt lgkmcnt(0)" ::: "memory")
; __device__ __forceinline__ unsigned pk2(float lo, float hi) { const pkf2_t v = {lo, hi}; const pkb2_t b = __builtin_convertvector(v, pkb2_t); return __builtin_bit_cast(unsigned, b); }
; __device__ __forceinline__ void p0_transpose_item(const float* W, int K, int N, bf16* WT, int row_off, LAS float* scr, int item, int lane) {
;     const int nblk = N / 32, kb = item / nblk, nb = item % nblk, k0 = 64 * kb, n0 = 32 * nb;
;     { const int kk = lane >> 3, n4 = (lane & 7) * 4; f32x4 v[8];
; #pragma unroll
;       for (int i = 0; i < 8; ++i) v[i] = *(const GAS f32x4*)(W + (size_t)(k0 + kk + 8 * i) * N + n0 + n4);
; #pragma unroll
;       for (int i = 0; i < 8; ++i) { LAS float* d = scr + (kk + 8 * i) * 33 + n4; d[0] = v[i][0]; d[1] = v[i][1]; d[2] = v[i][2]; d[3] = v[i][3]; } }
;     LDS_WAIT(); asm volatile("" ::: "memory");
;     const int c = lane & 7;
; #pragma unroll
;     for (int j = 0; j < 4; ++j) { const int n = (lane >> 3) + 8 * j; const LAS float* s = scr + (8 * c) * 33 + n;
;         v4u o; o.x = pk2(s[0 * 33], s[1 * 33]); o.y = pk2(s[2 * 33], s[3 * 33]); o.z = pk2(s[4 * 33], s[5 * 33]); o.w = pk2(s[6 * 33], s[7 * 33]);
;         *(GAS v4u*)(WT + (size_t)(row_off + n0 + n) * K + k0 + 8 * c) = o; }
;     LDS_WAIT(); asm volatile("" ::: "memory");
.LBB0_78:
	s_andn2_b64 vcc, exec, s[2:3]
	s_cbranch_vccnz .LBB0_80
	s_and_b32 s2, s11, 0x3c0
	s_and_b32 s3, s9, 0x1c0
	v_or_b32_e32 v2, s2, v16
	s_lshl_b32 s14, s3, 2
	v_lshl_add_u64 v[38:39], v[8:9], 0, s[14:15]
	v_lshlrev_b32_e32 v2, 11, v2
	v_lshl_add_u64 v[66:67], v[38:39], 0, v[2:3]
	v_add_co_u32_e32 v42, vcc, 0x4000, v66
	v_or_b32_e32 v2, s3, v16
	s_nop 0
	v_addc_co_u32_e32 v43, vcc, 0, v67, vcc
	v_add_co_u32_e32 v46, vcc, 0x8000, v66
	global_load_dwordx4 v[38:41], v[66:67], off nt
	s_nop 0
	global_load_dwordx4 v[42:45], v[42:43], off nt
	v_addc_co_u32_e32 v47, vcc, 0, v67, vcc
	v_add_co_u32_e32 v50, vcc, 0xc000, v66
	s_lshl_b32 s14, s2, 1
	s_nop 0
	v_addc_co_u32_e32 v51, vcc, 0, v67, vcc
	s_waitcnt lgkmcnt(0)
	v_add_co_u32_e32 v54, vcc, 0x10000, v66
	global_load_dwordx4 v[46:49], v[46:47], off nt
	s_nop 0
	global_load_dwordx4 v[50:53], v[50:51], off nt
	v_addc_co_u32_e32 v55, vcc, 0, v67, vcc
	v_add_co_u32_e32 v58, vcc, 0x14000, v66
	v_or_b32_e32 v37, s3, v18
	s_nop 0
	v_addc_co_u32_e32 v59, vcc, 0, v67, vcc
	global_load_dwordx4 v[54:57], v[54:55], off nt
	s_nop 0
	global_load_dwordx4 v[58:61], v[58:59], off nt
	v_add_co_u32_e32 v62, vcc, 0x18000, v66
	v_lshl_add_u64 v[70:71], v[10:11], 0, s[14:15]
	s_nop 0
	v_addc_co_u32_e32 v63, vcc, 0, v67, vcc
	global_load_dwordx4 v[62:65], v[62:63], off nt
	v_add_co_u32_e32 v66, vcc, 0x1c000, v66
	v_lshlrev_b32_e32 v2, 11, v2
	s_nop 0
	v_addc_co_u32_e32 v67, vcc, 0, v67, vcc
	global_load_dwordx4 v[66:69], v[66:67], off nt
	v_lshl_add_u64 v[72:73], v[70:71], 0, v[2:3]
	v_lshlrev_b32_e32 v2, 11, v37
	v_lshl_add_u64 v[74:75], v[70:71], 0, v[2:3]
	v_or_b32_e32 v2, s3, v19
	v_lshlrev_b32_e32 v2, 11, v2
	s_waitcnt vmcnt(7)
	ds_write2_b32 v22, v38, v39 offset1:1
	ds_write2_b32 v22, v40, v41 offset0:2 offset1:3
	s_waitcnt vmcnt(6)
	ds_write2_b32 v23, v42, v43 offset1:1
	ds_write2_b32 v24, v44, v45 offset1:1
	s_waitcnt vmcnt(5)
	ds_write2_b32 v25, v46, v47 offset1:1
	ds_write2_b32 v26, v48, v49 offset1:1
	s_waitcnt vmcnt(4)
	ds_write2_b32 v27, v50, v51 offset1:1
	ds_write2_b32 v28, v52, v53 offset1:1
	s_waitcnt vmcnt(3)
	ds_write2_b32 v29, v54, v55 offset1:1
	ds_write2_b32 v30, v56, v57 offset1:1
	s_waitcnt vmcnt(2)
	ds_write2_b32 v31, v58, v59 offset1:1
	ds_write2_b32 v32, v60, v61 offset1:1
	s_waitcnt vmcnt(1)
	ds_write2_b32 v33, v62, v63 offset1:1
	ds_write2_b32 v34, v64, v65 offset1:1
	s_waitcnt vmcnt(0)
	ds_write2_b32 v35, v66, v67 offset1:1
	ds_write2_b32 v36, v68, v69 offset1:1
	s_waitcnt lgkmcnt(0)
	ds_read2_b32 v[42:43], v21 offset0:33 offset1:41
	ds_read2_b32 v[44:45], v21 offset1:8
	ds_read2_b32 v[46:47], v21 offset0:66 offset1:74
	ds_read2_b32 v[48:49], v21 offset0:99 offset1:107
	ds_read2_b32 v[50:51], v21 offset0:132 offset1:140
	ds_read2_b32 v[52:53], v21 offset0:165 offset1:173
	ds_read2_b32 v[54:55], v21 offset0:198 offset1:206
	ds_read2_b32 v[56:57], v21 offset0:231 offset1:239
	ds_read2_b32 v[58:59], v21 offset0:49 offset1:57
	ds_read2_b32 v[60:61], v21 offset0:16 offset1:24
	ds_read2_b32 v[62:63], v21 offset0:82 offset1:90
	ds_read2_b32 v[64:65], v21 offset0:115 offset1:123
	ds_read2_b32 v[66:67], v21 offset0:148 offset1:156
	ds_read2_b32 v[68:69], v21 offset0:181 offset1:189
	ds_read2_b32 v[76:77], v21 offset0:214 offset1:222
	ds_read2_b32 v[78:79], v21 offset0:247 offset1:255
	s_waitcnt lgkmcnt(14)
	v_cvt_pk_bf16_f32 v38, v44, v42
	s_waitcnt lgkmcnt(12)
	v_cvt_pk_bf16_f32 v39, v46, v48
	s_waitcnt lgkmcnt(10)
	v_cvt_pk_bf16_f32 v40, v50, v52
	s_waitcnt lgkmcnt(8)
	v_cvt_pk_bf16_f32 v41, v54, v56
	v_cvt_pk_bf16_f32 v42, v45, v43
	v_cvt_pk_bf16_f32 v43, v47, v49
	v_cvt_pk_bf16_f32 v44, v51, v53
	v_cvt_pk_bf16_f32 v45, v55, v57
	global_store_dwordx4 v[72:73], v[38:41], off
	global_store_dwordx4 v[74:75], v[42:45], off
	s_waitcnt lgkmcnt(6)
	v_cvt_pk_bf16_f32 v38, v60, v58
	v_lshl_add_u64 v[42:43], v[70:71], 0, v[2:3]
	v_or_b32_e32 v2, s3, v20
	s_waitcnt lgkmcnt(4)
	v_cvt_pk_bf16_f32 v39, v62, v64
	s_waitcnt lgkmcnt(2)
	v_cvt_pk_bf16_f32 v40, v66, v68
	s_waitcnt lgkmcnt(0)
	v_cvt_pk_bf16_f32 v41, v76, v78
	v_lshlrev_b32_e32 v2, 11, v2
	global_store_dwordx4 v[42:43], v[38:41], off
	v_lshl_add_u64 v[42:43], v[70:71], 0, v[2:3]
	s_nop 0
	v_cvt_pk_bf16_f32 v38, v61, v59
	v_cvt_pk_bf16_f32 v39, v63, v65
	v_cvt_pk_bf16_f32 v40, v67, v69
	v_cvt_pk_bf16_f32 v41, v77, v79
	global_store_dwordx4 v[42:43], v[38:41], off
	s_waitcnt lgkmcnt(0)

; #define GAS __attribute__((address_space(1)))
; #define LAS __attribute__((address_space(3)))
; #define LDS_WAIT() asm volatile("s_waitcnt lgkmcnt(0)" ::: "memory")
; __device__ __forceinline__ unsigned pk2(float lo, float hi) { const pkf2_t v = {lo, hi}; const pkb2_t b = __builtin_convertvector(v, pkb2_t); return __builtin_bit_cast(unsigned, b); }
; __device__ __forceinline__ void p0_transpose_item2(const float* W, int K, int N, bf16* WT, int dst_row0, const float* gain, LAS float* scr, int kb, int nb, int lane) {
;     const int k0 = 64 * kb, n0 = 32 * nb;
;     const int c = lane & 7; float gg[8];
;     { const int kk = lane >> 3, n4 = (lane & 7) * 4; f32x4 v[8];
; #pragma unroll
;       for (int i = 0; i < 8; ++i) v[i] = *(const GAS f32x4*)(W + (size_t)(k0 + kk + 8 * i) * N + n0 + n4);
; #pragma unroll
;       for (int e = 0; e < 8; ++e) gg[e] = gain[k0 + 8 * c + e];
; #pragma unroll
;       for (int i = 0; i < 8; ++i) { LAS float* d = scr + (kk + 8 * i) * 33 + n4; d[0] = v[i][0]; d[1] = v[i][1]; d[2] = v[i][2]; d[3] = v[i][3]; } }
;     LDS_WAIT(); asm volatile("" ::: "memory");
; #pragma unroll
;     for (int j = 0; j < 4; ++j) { const int n = (lane >> 3) + 8 * j; const LAS float* s = scr + (8 * c) * 33 + n;
;         v4u o; o.x = pk2(s[0 * 33] * gg[0], s[1 * 33] * gg[1]); o.y = pk2(s[2 * 33] * gg[2], s[3 * 33] * gg[3]); o.z = pk2(s[4 * 33] * gg[4], s[5 * 33] * gg[5]); o.w = pk2(s[6 * 33] * gg[6], s[7 * 33] * gg[7]);
;         *(GAS v4u*)(WT + (size_t)(dst_row0 + n) * K + k0 + 8 * c) = o; }
;     LDS_WAIT(); asm volatile("" ::: "memory");
; }
.LBB0_81:
	s_andn2_b64 vcc, exec, s[2:3]
	s_cbranch_vccnz .LBB0_74
	s_mul_hi_i32 s2, s23, 0x66666667
	s_lshr_b32 s3, s2, 31
	s_ashr_i32 s2, s2, 5
	s_add_i32 s2, s2, s3
	s_mul_i32 s3, s2, 0xfffff600
	s_add_i32 s4, s9, s3
	s_lshl_b32 s2, s2, 6
	v_or_b32_e32 v2, s2, v16
	s_ashr_i32 s5, s4, 31
	v_lshl_add_u64 v[66:67], s[4:5], 2, v[12:13]
	v_or_b32_e32 v37, 8, v2
	v_mad_i64_i32 v[42:43], s[24:25], v37, s22, v[66:67]
	v_or_b32_e32 v37, 16, v2
	v_mad_i64_i32 v[46:47], s[24:25], v37, s22, v[66:67]
	v_or_b32_e32 v37, 24, v2
	v_mad_i64_i32 v[50:51], s[24:25], v37, s22, v[66:67]
	v_or_b32_e32 v37, 32, v2
	s_waitcnt lgkmcnt(0)
	v_mad_i64_i32 v[54:55], s[24:25], v37, s22, v[66:67]
	v_or_b32_e32 v37, 40, v2
	v_mad_i64_i32 v[38:39], s[24:25], v2, s22, v[66:67]
	v_mad_i64_i32 v[58:59], s[24:25], v37, s22, v[66:67]
	global_load_dwordx4 v[38:41], v[38:39], off nt
	s_nop 0
	global_load_dwordx4 v[42:45], v[42:43], off nt
	s_nop 0
	global_load_dwordx4 v[46:49], v[46:47], off nt
	s_nop 0
	global_load_dwordx4 v[50:53], v[50:51], off nt
	s_nop 0
	global_load_dwordx4 v[54:57], v[54:55], off nt
	s_nop 0
	global_load_dwordx4 v[58:61], v[58:59], off nt
	v_or_b32_e32 v70, s2, v17
	v_readlane_b32 s48, v254, 23
	v_or_b32_e32 v37, 48, v2
	v_or_b32_e32 v2, 56, v2
	v_ashrrev_i32_e32 v71, 31, v70
	v_readlane_b32 s49, v254, 24
	v_mad_i64_i32 v[62:63], s[24:25], v37, s22, v[66:67]
	v_mad_i64_i32 v[66:67], s[24:25], v2, s22, v[66:67]
	v_lshl_add_u64 v[74:75], v[70:71], 2, s[48:49]
	global_load_dwordx4 v[62:65], v[62:63], off nt
	v_add_u32_e32 v80, s4, v16
	global_load_dwordx4 v[66:69], v[66:67], off nt
	s_nop 0
	global_load_dwordx4 v[70:73], v[74:75], off nt
	s_nop 0
	global_load_dwordx4 v[74:77], v[74:75], off offset:16 nt
	s_ashr_i32 s3, s2, 31
	v_ashrrev_i32_e32 v81, 31, v80
	v_lshl_add_u64 v[78:79], s[2:3], 1, v[14:15]
	v_lshlrev_b64 v[82:83], 11, v[80:81]
	v_lshl_add_u64 v[82:83], v[78:79], 0, v[82:83]
	v_readlane_b32 s50, v254, 25
	v_readlane_b32 s51, v254, 26
	v_readlane_b32 s52, v254, 27
	v_readlane_b32 s53, v254, 28
	v_readlane_b32 s54, v254, 29
	v_readlane_b32 s55, v254, 30
	v_readlane_b32 s56, v254, 31
	v_readlane_b32 s57, v254, 32
	v_readlane_b32 s58, v254, 33
	v_readlane_b32 s59, v254, 34
	v_readlane_b32 s60, v254, 35
	v_readlane_b32 s61, v254, 36
	v_readlane_b32 s62, v254, 37
	v_readlane_b32 s63, v254, 38
	s_waitcnt vmcnt(9)
	ds_write2_b32 v22, v38, v39 offset1:1
	ds_write2_b32 v22, v40, v41 offset0:2 offset1:3
	s_waitcnt vmcnt(8)
	ds_write2_b32 v23, v42, v43 offset1:1
	ds_write2_b32 v24, v44, v45 offset1:1
	s_waitcnt vmcnt(7)
	ds_write2_b32 v25, v46, v47 offset1:1
	ds_write2_b32 v26, v48, v49 offset1:1
	s_waitcnt vmcnt(6)
	ds_write2_b32 v27, v50, v51 offset1:1
	ds_write2_b32 v28, v52, v53 offset1:1
	s_waitcnt vmcnt(5)
	ds_write2_b32 v29, v54, v55 offset1:1
	ds_write2_b32 v30, v56, v57 offset1:1
	s_waitcnt vmcnt(4)
	ds_write2_b32 v31, v58, v59 offset1:1
	ds_write2_b32 v32, v60, v61 offset1:1
	s_waitcnt vmcnt(3)
	ds_write2_b32 v33, v62, v63 offset1:1
	ds_write2_b32 v34, v64, v65 offset1:1
	s_waitcnt vmcnt(2)
	ds_write2_b32 v35, v66, v67 offset1:1
	ds_write2_b32 v36, v68, v69 offset1:1
	s_waitcnt lgkmcnt(0)
	ds_read2_b32 v[38:39], v21 offset0:33 offset1:41
	ds_read2_b32 v[40:41], v21 offset1:8
	ds_read2_b32 v[42:43], v21 offset0:66 offset1:74
	ds_read2_b32 v[44:45], v21 offset0:99 offset1:107
	ds_read2_b32 v[46:47], v21 offset0:132 offset1:140
	ds_read2_b32 v[48:49], v21 offset0:165 offset1:173
	ds_read2_b32 v[50:51], v21 offset0:198 offset1:206
	ds_read2_b32 v[52:53], v21 offset0:231 offset1:239
	s_waitcnt lgkmcnt(6)
	v_mov_b32_e32 v54, v40
	v_mov_b32_e32 v55, v38
	s_waitcnt lgkmcnt(5)
	v_mov_b32_e32 v56, v42
	s_waitcnt lgkmcnt(4)
	v_mov_b32_e32 v57, v44
	s_waitcnt lgkmcnt(3)
	v_mov_b32_e32 v58, v46
	s_waitcnt lgkmcnt(2)
	v_mov_b32_e32 v59, v48
	s_waitcnt lgkmcnt(1)
	v_mov_b32_e32 v60, v50
	s_waitcnt lgkmcnt(0)
	v_mov_b32_e32 v61, v52
	v_mov_b32_e32 v38, v41
	v_mov_b32_e32 v44, v43
	s_waitcnt vmcnt(1)
	v_pk_mul_f32 v[40:41], v[70:71], v[54:55]
	v_pk_mul_f32 v[42:43], v[72:73], v[56:57]
	s_waitcnt vmcnt(0)
	v_pk_mul_f32 v[54:55], v[74:75], v[58:59]
	v_pk_mul_f32 v[56:57], v[76:77], v[60:61]
	v_pk_mul_f32 v[58:59], v[70:71], v[38:39]
	v_cvt_pk_bf16_f32 v38, v40, v41
	v_cvt_pk_bf16_f32 v39, v42, v43
	v_cvt_pk_bf16_f32 v40, v54, v55
	v_cvt_pk_bf16_f32 v41, v56, v57
	v_mov_b32_e32 v48, v47
	v_pk_mul_f32 v[44:45], v[72:73], v[44:45]
	global_store_dwordx4 v[82:83], v[38:41], off
	v_mov_b32_e32 v52, v51
	v_cvt_pk_bf16_f32 v43, v44, v45
	v_pk_mul_f32 v[38:39], v[74:75], v[48:49]
	v_cvt_pk_bf16_f32 v42, v58, v59
	v_cvt_pk_bf16_f32 v44, v38, v39
	v_pk_mul_f32 v[38:39], v[76:77], v[52:53]
	ds_read2_b32 v[46:47], v21 offset0:16 offset1:24
	v_cvt_pk_bf16_f32 v45, v38, v39
	v_add_u32_e32 v38, 8, v80
	v_ashrrev_i32_e32 v39, 31, v38
	v_lshlrev_b64 v[38:39], 11, v[38:39]
	v_lshl_add_u64 v[38:39], v[78:79], 0, v[38:39]
	ds_read2_b32 v[48:49], v21 offset0:49 offset1:57
	global_store_dwordx4 v[38:39], v[42:45], off
	ds_read2_b32 v[42:43], v21 offset0:82 offset1:90
	ds_read2_b32 v[44:45], v21 offset0:115 offset1:123
	ds_read2_b32 v[50:51], v21 offset0:148 offset1:156
	ds_read2_b32 v[52:53], v21 offset0:181 offset1:189
	ds_read2_b32 v[54:55], v21 offset0:214 offset1:222
	ds_read2_b32 v[56:57], v21 offset0:247 offset1:255
	s_waitcnt lgkmcnt(7)
	v_mov_b32_e32 v38, v46
	s_waitcnt lgkmcnt(6)
	v_mov_b32_e32 v39, v48
	s_waitcnt lgkmcnt(5)
	v_mov_b32_e32 v40, v42
	s_waitcnt lgkmcnt(4)
	v_mov_b32_e32 v41, v44
	v_pk_mul_f32 v[38:39], v[70:71], v[38:39]
	v_pk_mul_f32 v[40:41], v[72:73], v[40:41]
	v_cvt_pk_bf16_f32 v38, v38, v39
	v_cvt_pk_bf16_f32 v39, v40, v41
	s_waitcnt lgkmcnt(3)
	v_mov_b32_e32 v40, v50
	s_waitcnt lgkmcnt(2)
	v_mov_b32_e32 v41, v52
	s_waitcnt lgkmcnt(1)
	v_mov_b32_e32 v58, v54
	s_waitcnt lgkmcnt(0)
	v_mov_b32_e32 v59, v56
	v_pk_mul_f32 v[40:41], v[74:75], v[40:41]
	v_pk_mul_f32 v[58:59], v[76:77], v[58:59]
	v_cvt_pk_bf16_f32 v40, v40, v41
	v_cvt_pk_bf16_f32 v41, v58, v59
	v_add_u32_e32 v58, 16, v80
	v_ashrrev_i32_e32 v59, 31, v58
	v_lshlrev_b64 v[58:59], 11, v[58:59]
	v_lshl_add_u64 v[58:59], v[78:79], 0, v[58:59]
	v_mov_b32_e32 v48, v47
	v_mov_b32_e32 v44, v43
	global_store_dwordx4 v[58:59], v[38:41], off
	v_mov_b32_e32 v52, v51
	v_mov_b32_e32 v56, v55
	v_pk_mul_f32 v[38:39], v[70:71], v[48:49]
	v_pk_mul_f32 v[40:41], v[72:73], v[44:45]
	v_cvt_pk_bf16_f32 v38, v38, v39
	v_cvt_pk_bf16_f32 v39, v40, v41
	v_pk_mul_f32 v[40:41], v[74:75], v[52:53]
	v_pk_mul_f32 v[42:43], v[76:77], v[56:57]
	v_cvt_pk_bf16_f32 v40, v40, v41
	v_cvt_pk_bf16_f32 v41, v42, v43
	v_add_u32_e32 v42, 24, v80
	v_ashrrev_i32_e32 v43, 31, v42
	v_lshlrev_b64 v[42:43], 11, v[42:43]
	v_lshl_add_u64 v[42:43], v[78:79], 0, v[42:43]
	global_store_dwordx4 v[42:43], v[38:41], off
	s_waitcnt lgkmcnt(0)
	s_branch .LBB0_74

; #define GAS __attribute__((address_space(1)))
; #define LAS __attribute__((address_space(3)))
; #define LDS_WAIT() asm volatile("s_waitcnt lgkmcnt(0)" ::: "memory")
; __device__ __forceinline__ unsigned pk2(float lo, float hi) { const pkf2_t v = {lo, hi}; const pkb2_t b = __builtin_convertvector(v, pkb2_t); return __builtin_bit_cast(unsigned, b); }
; __device__ __forceinline__ void p0_transpose_item(const float* W, int K, int N, bf16* WT, int row_off, LAS float* scr, int item, int lane) {
;     const int nblk = N / 32, kb = item / nblk, nb = item % nblk, k0 = 64 * kb, n0 = 32 * nb;
;     { const int kk = lane >> 3, n4 = (lane & 7) * 4; f32x4 v[8];
; #pragma unroll
;       for (int i = 0; i < 8; ++i) v[i] = *(const GAS f32x4*)(W + (size_t)(k0 + kk + 8 * i) * N + n0 + n4);
; #pragma unroll
;       for (int i = 0; i < 8; ++i) { LAS float* d = scr + (kk + 8 * i) * 33 + n4; d[0] = v[i][0]; d[1] = v[i][1]; d[2] = v[i][2]; d[3] = v[i][3]; } }
;     LDS_WAIT(); asm volatile("" ::: "memory");
;     const int c = lane & 7;
; #pragma unroll
;     for (int j = 0; j < 4; ++j) { const int n = (lane >> 3) + 8 * j; const LAS float* s = scr + (8 * c) * 33 + n;
;         v4u o; o.x = pk2(s[0 * 33], s[1 * 33]); o.y = pk2(s[2 * 33], s[3 * 33]); o.z = pk2(s[4 * 33], s[5 * 33]); o.w = pk2(s[6 * 33], s[7 * 33]);
;         *(GAS v4u*)(WT + (size_t)(row_off + n0 + n) * K + k0 + 8 * c) = o; }
;     LDS_WAIT(); asm volatile("" ::: "memory");
.LBB0_86:
	s_cmpk_gt_i32 s10, 0x1ff
	s_mov_b64 s[2:3], -1
	s_cbranch_scc0 .LBB0_88
	s_add_i32 s0, s5, 0x1fc00
	s_and_b32 s2, s0, 0x1ffc0
	s_and_b32 s3, s8, 0x3c0
	v_or_b32_e32 v2, s2, v12
	s_lshl_b32 s0, s3, 2
	v_lshl_add_u64 v[32:33], v[4:5], 0, s[0:1]
	v_lshlrev_b32_e32 v2, 12, v2
	v_lshl_add_u64 v[60:61], v[32:33], 0, v[2:3]
	v_add_co_u32_e32 v36, vcc, 0x8000, v60
	v_or_b32_e32 v2, s3, v12
	s_nop 0
	v_addc_co_u32_e32 v37, vcc, 0, v61, vcc
	v_add_co_u32_e32 v40, vcc, 0x10000, v60
	global_load_dwordx4 v[32:35], v[60:61], off nt
	s_nop 0
	global_load_dwordx4 v[36:39], v[36:37], off nt
	v_addc_co_u32_e32 v41, vcc, 0, v61, vcc
	v_add_co_u32_e32 v44, vcc, 0x18000, v60
	s_lshl_b32 s0, s2, 1
	s_nop 0
	v_addc_co_u32_e32 v45, vcc, 0, v61, vcc
	v_add_co_u32_e32 v48, vcc, 0x20000, v60
	global_load_dwordx4 v[40:43], v[40:41], off nt
	s_nop 0
	global_load_dwordx4 v[44:47], v[44:45], off nt
	v_addc_co_u32_e32 v49, vcc, 0, v61, vcc
	v_add_co_u32_e32 v52, vcc, 0x28000, v60
	v_or_b32_e32 v68, s3, v13
	s_nop 0
	v_addc_co_u32_e32 v53, vcc, 0, v61, vcc
	global_load_dwordx4 v[48:51], v[48:49], off nt
	s_waitcnt lgkmcnt(0)
	global_load_dwordx4 v[52:55], v[52:53], off nt
	v_add_co_u32_e32 v56, vcc, 0x30000, v60
	v_lshl_add_u64 v[64:65], v[6:7], 0, s[0:1]
	s_nop 0
	v_addc_co_u32_e32 v57, vcc, 0, v61, vcc
	global_load_dwordx4 v[56:59], v[56:57], off nt
	v_add_co_u32_e32 v60, vcc, 0x38000, v60
	v_mul_u32_u24_e32 v2, 0x1600, v2
	s_nop 0
	v_addc_co_u32_e32 v61, vcc, 0, v61, vcc
	global_load_dwordx4 v[60:63], v[60:61], off nt
	v_lshl_add_u64 v[66:67], v[64:65], 0, v[2:3]
	v_mul_u32_u24_e32 v2, 0x1600, v68
	v_lshl_add_u64 v[68:69], v[64:65], 0, v[2:3]
	v_or_b32_e32 v2, s3, v14
	v_mul_u32_u24_e32 v2, 0x1600, v2
	s_waitcnt vmcnt(7)
	ds_write2_b32 v17, v32, v33 offset1:1
	ds_write2_b32 v17, v34, v35 offset0:2 offset1:3
	s_waitcnt vmcnt(6)
	ds_write2_b32 v18, v36, v37 offset1:1
	ds_write2_b32 v19, v38, v39 offset1:1
	s_waitcnt vmcnt(5)
	ds_write2_b32 v20, v40, v41 offset1:1
	ds_write2_b32 v21, v42, v43 offset1:1
	s_waitcnt vmcnt(4)
	ds_write2_b32 v22, v44, v45 offset1:1
	ds_write2_b32 v23, v46, v47 offset1:1
	s_waitcnt vmcnt(3)
	ds_write2_b32 v24, v48, v49 offset1:1
	ds_write2_b32 v25, v50, v51 offset1:1
	s_waitcnt vmcnt(2)
	ds_write2_b32 v26, v52, v53 offset1:1
	ds_write2_b32 v27, v54, v55 offset1:1
	s_waitcnt vmcnt(1)
	ds_write2_b32 v28, v56, v57 offset1:1
	ds_write2_b32 v29, v58, v59 offset1:1
	s_waitcnt vmcnt(0)
	ds_write2_b32 v30, v60, v61 offset1:1
	ds_write2_b32 v31, v62, v63 offset1:1
	s_waitcnt lgkmcnt(0)
	ds_read2_b32 v[36:37], v16 offset0:33 offset1:41
	ds_read2_b32 v[38:39], v16 offset1:8
	ds_read2_b32 v[40:41], v16 offset0:66 offset1:74
	ds_read2_b32 v[42:43], v16 offset0:99 offset1:107
	ds_read2_b32 v[44:45], v16 offset0:132 offset1:140
	ds_read2_b32 v[46:47], v16 offset0:165 offset1:173
	ds_read2_b32 v[48:49], v16 offset0:198 offset1:206
	ds_read2_b32 v[50:51], v16 offset0:231 offset1:239
	ds_read2_b32 v[52:53], v16 offset0:16 offset1:24
	ds_read2_b32 v[54:55], v16 offset0:49 offset1:57
	ds_read2_b32 v[56:57], v16 offset0:82 offset1:90
	ds_read2_b32 v[58:59], v16 offset0:115 offset1:123
	ds_read2_b32 v[60:61], v16 offset0:148 offset1:156
	ds_read2_b32 v[62:63], v16 offset0:181 offset1:189
	ds_read2_b32 v[70:71], v16 offset0:214 offset1:222
	ds_read2_b32 v[72:73], v16 offset0:247 offset1:255
	s_waitcnt lgkmcnt(14)
	v_cvt_pk_bf16_f32 v32, v38, v36
	s_waitcnt lgkmcnt(12)
	v_cvt_pk_bf16_f32 v33, v40, v42
	s_waitcnt lgkmcnt(10)
	v_cvt_pk_bf16_f32 v34, v44, v46
	s_waitcnt lgkmcnt(8)
	v_cvt_pk_bf16_f32 v35, v48, v50
	v_cvt_pk_bf16_f32 v36, v39, v37
	v_cvt_pk_bf16_f32 v37, v41, v43
	v_cvt_pk_bf16_f32 v38, v45, v47
	v_cvt_pk_bf16_f32 v39, v49, v51
	global_store_dwordx4 v[66:67], v[32:35], off
	global_store_dwordx4 v[68:69], v[36:39], off
	s_waitcnt lgkmcnt(6)
	v_cvt_pk_bf16_f32 v32, v52, v54
	v_lshl_add_u64 v[36:37], v[64:65], 0, v[2:3]
	v_or_b32_e32 v2, s3, v15
	s_waitcnt lgkmcnt(4)
	v_cvt_pk_bf16_f32 v33, v56, v58
	s_waitcnt lgkmcnt(2)
	v_cvt_pk_bf16_f32 v34, v60, v62
	s_waitcnt lgkmcnt(0)
	v_cvt_pk_bf16_f32 v35, v70, v72
	v_mul_u32_u24_e32 v2, 0x1600, v2
	global_store_dwordx4 v[36:37], v[32:35], off
	v_lshl_add_u64 v[36:37], v[64:65], 0, v[2:3]
	s_mov_b64 s[2:3], 0
	v_cvt_pk_bf16_f32 v32, v53, v55
	v_cvt_pk_bf16_f32 v33, v57, v59
	v_cvt_pk_bf16_f32 v34, v61, v63
	v_cvt_pk_bf16_f32 v35, v71, v73
	global_store_dwordx4 v[36:37], v[32:35], off
	s_waitcnt lgkmcnt(0)
; #define GAS __attribute__((address_space(1)))
; #define LAS __attribute__((address_space(3)))
; #define LDS_WAIT() asm volatile("s_waitcnt lgkmcnt(0)" ::: "memory")
; __device__ __forceinline__ unsigned pk2(float lo, float hi) { const pkf2_t v = {lo, hi}; const pkb2_t b = __builtin_convertvector(v, pkb2_t); return __builtin_bit_cast(unsigned, b); }
; __device__ __forceinline__ void p0_transpose_item(const float* W, int K, int N, bf16* WT, int row_off, LAS float* scr, int item, int lane) {
;     const int nblk = N / 32, kb = item / nblk, nb = item % nblk, k0 = 64 * kb, n0 = 32 * nb;
;     { const int kk = lane >> 3, n4 = (lane & 7) * 4; f32x4 v[8];
; #pragma unroll
;       for (int i = 0; i < 8; ++i) v[i] = *(const GAS f32x4*)(W + (size_t)(k0 + kk + 8 * i) * N + n0 + n4);
; #pragma unroll
;       for (int i = 0; i < 8; ++i) { LAS float* d = scr + (kk + 8 * i) * 33 + n4; d[0] = v[i][0]; d[1] = v[i][1]; d[2] = v[i][2]; d[3] = v[i][3]; } }
;     LDS_WAIT(); asm volatile("" ::: "memory");
;     const int c = lane & 7;
; #pragma unroll
;     for (int j = 0; j < 4; ++j) { const int n = (lane >> 3) + 8 * j; const LAS float* s = scr + (8 * c) * 33 + n;
;         v4u o; o.x = pk2(s[0 * 33], s[1 * 33]); o.y = pk2(s[2 * 33], s[3 * 33]); o.z = pk2(s[4 * 33], s[5 * 33]); o.w = pk2(s[6 * 33], s[7 * 33]);
;         *(GAS v4u*)(WT + (size_t)(row_off + n0 + n) * K + k0 + 8 * c) = o; }
;     LDS_WAIT(); asm volatile("" ::: "memory");
.LBB0_88:
	s_andn2_b64 vcc, exec, s[2:3]
	s_cbranch_vccnz .LBB0_85
	s_cmpk_lt_i32 s10, 0x80
	s_cbranch_scc1 .LBB0_85
	s_and_b32 s2, s5, 0x1ffc0
	s_and_b32 s3, s8, 0x3c0
	v_or_b32_e32 v2, s2, v12
	s_lshl_b32 s0, s3, 2
	v_lshl_add_u64 v[32:33], v[8:9], 0, s[0:1]
	v_lshlrev_b32_e32 v2, 12, v2
	v_lshl_add_u64 v[60:61], v[32:33], 0, v[2:3]
	v_add_co_u32_e32 v36, vcc, 0x8000, v60
	v_or_b32_e32 v2, s3, v12
	s_nop 0
	v_addc_co_u32_e32 v37, vcc, 0, v61, vcc
	v_add_co_u32_e32 v40, vcc, 0x10000, v60
	global_load_dwordx4 v[32:35], v[60:61], off nt
	s_nop 0
	global_load_dwordx4 v[36:39], v[36:37], off nt
	v_addc_co_u32_e32 v41, vcc, 0, v61, vcc
	v_add_co_u32_e32 v44, vcc, 0x18000, v60
	s_lshl_b32 s0, s2, 1
	s_nop 0
	v_addc_co_u32_e32 v45, vcc, 0, v61, vcc
	v_add_co_u32_e32 v48, vcc, 0x20000, v60
	global_load_dwordx4 v[40:43], v[40:41], off nt
	s_nop 0
	global_load_dwordx4 v[44:47], v[44:45], off nt
	v_addc_co_u32_e32 v49, vcc, 0, v61, vcc
	v_add_co_u32_e32 v52, vcc, 0x28000, v60
	v_or_b32_e32 v68, s3, v13
	s_nop 0
	v_addc_co_u32_e32 v53, vcc, 0, v61, vcc
	global_load_dwordx4 v[48:51], v[48:49], off nt
	s_waitcnt lgkmcnt(0)
	global_load_dwordx4 v[52:55], v[52:53], off nt
	v_add_co_u32_e32 v56, vcc, 0x30000, v60
	v_lshl_add_u64 v[64:65], v[10:11], 0, s[0:1]
	s_nop 0
	v_addc_co_u32_e32 v57, vcc, 0, v61, vcc
	global_load_dwordx4 v[56:59], v[56:57], off nt
	v_add_co_u32_e32 v60, vcc, 0x38000, v60
	v_lshlrev_b32_e32 v2, 11, v2
	s_nop 0
	v_addc_co_u32_e32 v61, vcc, 0, v61, vcc
	global_load_dwordx4 v[60:63], v[60:61], off nt
	v_lshl_add_u64 v[66:67], v[64:65], 0, v[2:3]
	v_lshlrev_b32_e32 v2, 11, v68
	v_lshl_add_u64 v[68:69], v[64:65], 0, v[2:3]
	v_or_b32_e32 v2, s3, v14
	v_lshlrev_b32_e32 v2, 11, v2
	s_waitcnt vmcnt(7)
	ds_write2_b32 v17, v32, v33 offset1:1
	ds_write2_b32 v17, v34, v35 offset0:2 offset1:3
	s_waitcnt vmcnt(6)
	ds_write2_b32 v18, v36, v37 offset1:1
	ds_write2_b32 v19, v38, v39 offset1:1
	s_waitcnt vmcnt(5)
	ds_write2_b32 v20, v40, v41 offset1:1
	ds_write2_b32 v21, v42, v43 offset1:1
	s_waitcnt vmcnt(4)
	ds_write2_b32 v22, v44, v45 offset1:1
	ds_write2_b32 v23, v46, v47 offset1:1
	s_waitcnt vmcnt(3)
	ds_write2_b32 v24, v48, v49 offset1:1
	ds_write2_b32 v25, v50, v51 offset1:1
	s_waitcnt vmcnt(2)
	ds_write2_b32 v26, v52, v53 offset1:1
	ds_write2_b32 v27, v54, v55 offset1:1
	s_waitcnt vmcnt(1)
	ds_write2_b32 v28, v56, v57 offset1:1
	ds_write2_b32 v29, v58, v59 offset1:1
	s_waitcnt vmcnt(0)
	ds_write2_b32 v30, v60, v61 offset1:1
	ds_write2_b32 v31, v62, v63 offset1:1
	s_waitcnt lgkmcnt(0)
	ds_read2_b32 v[36:37], v16 offset0:33 offset1:41
	ds_read2_b32 v[38:39], v16 offset1:8
	ds_read2_b32 v[40:41], v16 offset0:66 offset1:74
	ds_read2_b32 v[42:43], v16 offset0:99 offset1:107
	ds_read2_b32 v[44:45], v16 offset0:132 offset1:140
	ds_read2_b32 v[46:47], v16 offset0:165 offset1:173
	ds_read2_b32 v[48:49], v16 offset0:198 offset1:206
	ds_read2_b32 v[50:51], v16 offset0:231 offset1:239
	ds_read2_b32 v[52:53], v16 offset0:49 offset1:57
	ds_read2_b32 v[54:55], v16 offset0:16 offset1:24
	ds_read2_b32 v[56:57], v16 offset0:82 offset1:90
	ds_read2_b32 v[58:59], v16 offset0:115 offset1:123
	ds_read2_b32 v[60:61], v16 offset0:148 offset1:156
	ds_read2_b32 v[62:63], v16 offset0:181 offset1:189
	ds_read2_b32 v[70:71], v16 offset0:214 offset1:222
	ds_read2_b32 v[72:73], v16 offset0:247 offset1:255
	s_waitcnt lgkmcnt(14)
	v_cvt_pk_bf16_f32 v32, v38, v36
	s_waitcnt lgkmcnt(12)
	v_cvt_pk_bf16_f32 v33, v40, v42
	s_waitcnt lgkmcnt(10)
	v_cvt_pk_bf16_f32 v34, v44, v46
	s_waitcnt lgkmcnt(8)
	v_cvt_pk_bf16_f32 v35, v48, v50
	v_cvt_pk_bf16_f32 v36, v39, v37
	v_cvt_pk_bf16_f32 v37, v41, v43
	v_cvt_pk_bf16_f32 v38, v45, v47
	v_cvt_pk_bf16_f32 v39, v49, v51
	global_store_dwordx4 v[66:67], v[32:35], off
	global_store_dwordx4 v[68:69], v[36:39], off
	s_waitcnt lgkmcnt(6)
	v_cvt_pk_bf16_f32 v32, v54, v52
	v_lshl_add_u64 v[36:37], v[64:65], 0, v[2:3]
	v_or_b32_e32 v2, s3, v15
	s_waitcnt lgkmcnt(4)
	v_cvt_pk_bf16_f32 v33, v56, v58
	s_waitcnt lgkmcnt(2)
	v_cvt_pk_bf16_f32 v34, v60, v62
	s_waitcnt lgkmcnt(0)
	v_cvt_pk_bf16_f32 v35, v70, v72
	v_lshlrev_b32_e32 v2, 11, v2
	global_store_dwordx4 v[36:37], v[32:35], off
	v_lshl_add_u64 v[36:37], v[64:65], 0, v[2:3]
	s_nop 0
	v_cvt_pk_bf16_f32 v32, v55, v53
	v_cvt_pk_bf16_f32 v33, v57, v59
	v_cvt_pk_bf16_f32 v34, v61, v63
	v_cvt_pk_bf16_f32 v35, v71, v73
	global_store_dwordx4 v[36:37], v[32:35], off
	s_waitcnt lgkmcnt(0)
	s_branch .LBB0_85
